# shared-LDS attention: scalar bookkeeping before the per-step barrier; barriers dropped for the steps after the last shared window row (context steps run free)
# baseline (speedup 1.0000x reference)
.LBB0_465:
	v_add_f32_e32 v1, v1, v4
	v_mul_f32_e32 v4, 0x4f800000, v1
	v_cmp_gt_f32_e32 vcc, s70, v1
	v_add_f32_e32 v2, v2, v3
	v_mul_f32_e32 v3, 0x4f800000, v2
	v_cndmask_b32_e32 v1, v1, v4, vcc
	v_sqrt_f32_e32 v4, v1
	s_mul_i32 s82, s82, 0x88000
	s_lshl_b32 s81, s7, 1
	s_mov_b32 s42, s26
	v_add_u32_e32 v9, -1, v4
	v_fma_f32 v10, -v9, v4, v1
	v_cmp_ge_f32_e64 s[0:1], 0, v10
	v_add_u32_e32 v10, 1, v4
	s_mov_b32 s43, s27
	v_cndmask_b32_e64 v9, v4, v9, s[0:1]
	v_fma_f32 v4, -v10, v4, v1
	v_cmp_lt_f32_e64 s[0:1], 0, v4
	s_or_b32 s20, s5, 1
	s_and_b32 s4, s4, 15
	v_cndmask_b32_e64 v4, v9, v10, s[0:1]
	v_mul_f32_e32 v9, 0x37800000, v4
	v_cndmask_b32_e32 v4, v4, v9, vcc
	v_cmp_gt_f32_e32 vcc, s70, v2
	v_cmp_class_f32_e64 s[0:1], v1, v237
	s_lshl_b32 s4, s4, 10
	v_cndmask_b32_e32 v2, v2, v3, vcc
	v_sqrt_f32_e32 v3, v2
	v_cndmask_b32_e64 v1, v4, v1, s[0:1]
	s_waitcnt lgkmcnt(8)
	v_fma_f32 v1, v227, v1, v228
	v_mov_b32_e32 v224, 0
	v_add_u32_e32 v4, -1, v3
	v_fma_f32 v9, -v4, v3, v2
	v_cmp_ge_f32_e64 s[0:1], 0, v9
	v_add_u32_e32 v9, 1, v3
	s_mov_b32 s92, 0
	v_cndmask_b32_e64 v4, v3, v4, s[0:1]
	v_fma_f32 v3, -v9, v3, v2
	v_cmp_lt_f32_e64 s[0:1], 0, v3
	s_add_i32 s83, s83, 20
	s_add_i32 s84, s75, 4
	v_cndmask_b32_e64 v3, v4, v9, s[0:1]
	v_mul_f32_e32 v4, 0x37800000, v3
	v_cndmask_b32_e32 v3, v3, v4, vcc
	v_add_f32_e32 v4, v5, v6
	v_mul_f32_e32 v5, 0x4f800000, v4
	v_cmp_gt_f32_e32 vcc, s70, v4
	v_cmp_class_f32_e64 s[0:1], v2, v237
	v_mov_b32_e32 v225, v224
	v_cndmask_b32_e32 v4, v4, v5, vcc
	v_sqrt_f32_e32 v5, v4
	v_cndmask_b32_e64 v2, v3, v2, s[0:1]
	v_fma_f32 v2, v227, v2, v228
	v_max3_f32 v1, v1, 0, v2
	v_add_u32_e32 v2, -1, v5
	v_fma_f32 v3, -v2, v5, v4
	v_cmp_ge_f32_e64 s[0:1], 0, v3
	v_add_u32_e32 v3, 1, v5
	v_mov_b32_e32 v222, v224
	v_cndmask_b32_e64 v2, v5, v2, s[0:1]
	v_fma_f32 v5, -v3, v5, v4
	v_cmp_lt_f32_e64 s[0:1], 0, v5
	v_mov_b32_e32 v223, v224
	s_nop 0
	v_cndmask_b32_e64 v2, v2, v3, s[0:1]
	v_mul_f32_e32 v3, 0x37800000, v2
	s_lshl_b32 s0, s8, 1
	v_cndmask_b32_e32 v2, v2, v3, vcc
	v_cmp_class_f32_e32 vcc, v4, v237
	v_add_f32_e32 v3, v7, v8
	s_add_i32 s0, s0, s82
	v_cndmask_b32_e32 v2, v2, v4, vcc
	v_mul_f32_e32 v4, 0x4f800000, v3
	v_cmp_gt_f32_e32 vcc, s70, v3
	s_add_i32 s7, s0, 0x44000
	s_add_i32 s1, s0, 0x4c800
	v_cndmask_b32_e32 v3, v3, v4, vcc
	s_add_i32 s9, s0, 0x8800
	v_sqrt_f32_e32 v52, v3
	v_fma_f32 v2, v227, v2, v228
	v_add_u32_e32 v53, -1, v52
	v_fma_f32 v54, -v53, v52, v3
	v_cmp_ge_f32_e64 s[0:1], 0, v54
	v_add_u32_e32 v54, 1, v52
	s_nop 0
	v_cndmask_b32_e64 v53, v52, v53, s[0:1]
	v_fma_f32 v52, -v54, v52, v3
	v_cmp_lt_f32_e64 s[0:1], 0, v52
	s_nop 1
	v_cndmask_b32_e64 v52, v53, v54, s[0:1]
	v_mul_f32_e32 v53, 0x37800000, v52
	v_cndmask_b32_e32 v52, v52, v53, vcc
	v_cmp_class_f32_e32 vcc, v3, v237
	s_nop 1
	v_cndmask_b32_e32 v3, v52, v3, vcc
	v_fma_f32 v3, v227, v3, v228
	v_max3_f32 v239, v1, v2, v3
	v_add_u32_e32 v1, s59, v232
	v_sub_u32_e32 v1, v229, v1
	v_add_u32_e32 v2, 15, v1
	v_cmp_gt_u32_e64 s[0:1], 16, v2
	v_add_u32_e32 v2, 14, v1
	v_cmp_gt_u32_e64 s[6:7], 16, v2
	v_add_u32_e32 v2, 13, v1
	v_cmp_gt_u32_e64 s[8:9], 16, v2
	v_add_u32_e32 v2, 12, v1
	v_cmp_gt_u32_e64 s[10:11], 16, v2
	v_add_u32_e32 v2, 11, v1
	v_cmp_gt_u32_e64 s[12:13], 16, v2
	v_add_u32_e32 v2, 10, v1
	v_cmp_gt_u32_e64 s[14:15], 16, v2
	v_add_u32_e32 v2, 9, v1
	v_add_u32_e32 v1, 8, v1
	v_cmp_gt_u32_e64 s[18:19], 16, v1
	v_sub_u32_e64 v1, s20, 4 clamp
	v_cmp_gt_u32_e64 s[16:17], 16, v2
	v_readfirstlane_b32 s20, v1
	s_min_u32 s85, s20, 56
	s_or_b32 s20, s5, 2
	v_sub_u32_e64 v1, s20, 4 clamp
	s_or_b32 s5, s5, 3
	v_readfirstlane_b32 s20, v1
	v_sub_u32_e64 v1, s5, 4 clamp
	s_min_u32 s87, s20, 56
	v_readfirstlane_b32 s5, v1
	s_min_u32 s89, s5, 56
	s_lshl_b32 s5, s75, 8
	s_lshl_b32 s20, s59, 2
	s_or_b32 s5, s5, s20
	v_lshrrev_b32_e32 v85, 4, v226
	v_and_b32_e32 v86, 15, v226
	v_lshlrev_b32_e32 v233, 9, v85
	v_lshl_add_u32 v233, v86, 4, v233
	v_lshlrev_b32_e32 v234, 4, v226
	s_lshl_b32 s97, s59, 3
	s_lshl_b32 s90, s59, 5
	s_add_u32 s90, s90, 0x2000
	s_sub_i32 s4, s5, s4
	v_add_u32_e32 v240, s4, v236
	ds_read2_b32 v[204:205], v240 offset0:192 offset1:193
	ds_read2_b32 v[206:207], v240 offset0:194 offset1:195
	ds_read2_b32 v[208:209], v240 offset0:196 offset1:197
	ds_read2_b32 v[210:211], v240 offset0:198 offset1:199
	ds_read2_b32 v[80:81], v240 offset0:128 offset1:129
	ds_read2_b32 v[82:83], v240 offset0:130 offset1:131
	ds_read2_b32 v[84:85], v240 offset0:132 offset1:133
	ds_read2_b32 v[86:87], v240 offset0:134 offset1:135
	ds_read2_b32 v[180:181], v240 offset0:64 offset1:65
	ds_read2_b32 v[182:183], v240 offset0:66 offset1:67
	ds_read2_b32 v[184:185], v240 offset0:68 offset1:69
	ds_read2_b32 v[186:187], v240 offset0:70 offset1:71
	ds_read2_b32 v[212:213], v240 offset0:0 offset1:1
	ds_read2_b32 v[214:215], v240 offset0:2 offset1:3
	ds_read2_b32 v[242:243], v240 offset0:4 offset1:5
	ds_read2_b32 v[244:245], v240 offset0:6 offset1:7
	v_xor_b32_e32 v76, 0x80000000, v239
	v_xor_b32_e32 v77, 0x80000000, v239
	v_xor_b32_e32 v78, 0x80000000, v239
	v_xor_b32_e32 v79, 0x80000000, v239
	v_mov_b32_e32 v96, 0
	v_mov_b32_e32 v97, 0
	v_mov_b32_e32 v98, 0
	v_mov_b32_e32 v99, 0
	v_mov_b32_e32 v88, 0
	v_mov_b32_e32 v89, 0
	v_mov_b32_e32 v90, 0
	v_mov_b32_e32 v91, 0
	v_mov_b32_e32 v72, 0
	v_mov_b32_e32 v73, 0
	v_mov_b32_e32 v74, 0
	v_mov_b32_e32 v75, 0
	v_mov_b32_e32 v68, 0
	v_mov_b32_e32 v69, 0
	v_mov_b32_e32 v70, 0
	v_mov_b32_e32 v71, 0
	v_mov_b32_e32 v222, 0
	v_mov_b32_e32 v64, 0
	v_mov_b32_e32 v65, 0
	v_mov_b32_e32 v66, 0
	v_mov_b32_e32 v67, 0
	v_mov_b32_e32 v60, 0
	v_mov_b32_e32 v61, 0
	v_mov_b32_e32 v62, 0
	v_mov_b32_e32 v63, 0
	v_mov_b32_e32 v56, 0
	v_mov_b32_e32 v57, 0
	v_mov_b32_e32 v58, 0
	v_mov_b32_e32 v59, 0
	v_mov_b32_e32 v52, 0
	v_mov_b32_e32 v53, 0
	v_mov_b32_e32 v54, 0
	v_mov_b32_e32 v55, 0
	v_mov_b32_e32 v223, 0
	v_mov_b32_e32 v128, 0
	v_mov_b32_e32 v129, 0
	v_mov_b32_e32 v130, 0
	v_mov_b32_e32 v131, 0
	v_mov_b32_e32 v124, 0
	v_mov_b32_e32 v125, 0
	v_mov_b32_e32 v126, 0
	v_mov_b32_e32 v127, 0
	v_mov_b32_e32 v120, 0
	v_mov_b32_e32 v121, 0
	v_mov_b32_e32 v122, 0
	v_mov_b32_e32 v123, 0
	v_mov_b32_e32 v116, 0
	v_mov_b32_e32 v117, 0
	v_mov_b32_e32 v118, 0
	v_mov_b32_e32 v119, 0
	v_mov_b32_e32 v224, 0
	v_mov_b32_e32 v112, 0
	v_mov_b32_e32 v113, 0
	v_mov_b32_e32 v114, 0
	v_mov_b32_e32 v115, 0
	v_mov_b32_e32 v108, 0
	v_mov_b32_e32 v109, 0
	v_mov_b32_e32 v110, 0
	v_mov_b32_e32 v111, 0
	v_mov_b32_e32 v104, 0
	v_mov_b32_e32 v105, 0
	v_mov_b32_e32 v106, 0
	v_mov_b32_e32 v107, 0
	v_mov_b32_e32 v100, 0
	v_mov_b32_e32 v101, 0
	v_mov_b32_e32 v102, 0
	v_mov_b32_e32 v103, 0
	v_mov_b32_e32 v225, 0
	s_waitcnt lgkmcnt(0)
	v_sub_f32_e32 v204, v204, v239
	v_sub_f32_e32 v205, v205, v239
	v_sub_f32_e32 v206, v206, v239
	v_sub_f32_e32 v207, v207, v239
	v_sub_f32_e32 v208, v208, v239
	v_sub_f32_e32 v209, v209, v239
	v_sub_f32_e32 v210, v210, v239
	v_sub_f32_e32 v211, v211, v239
	v_cndmask_b32_e64 v204, v238, v204, s[0:1]
	v_cndmask_b32_e64 v205, v238, v205, s[6:7]
	v_cndmask_b32_e64 v206, v238, v206, s[8:9]
	v_cndmask_b32_e64 v207, v238, v207, s[10:11]
	v_cndmask_b32_e64 v208, v238, v208, s[12:13]
	v_cndmask_b32_e64 v209, v238, v209, s[14:15]
	v_cndmask_b32_e64 v210, v238, v210, s[16:17]
	v_cndmask_b32_e64 v211, v238, v211, s[18:19]
	v_sub_f32_e32 v80, v80, v239
	v_sub_f32_e32 v81, v81, v239
	v_sub_f32_e32 v82, v82, v239
	v_sub_f32_e32 v83, v83, v239
	v_sub_f32_e32 v84, v84, v239
	v_sub_f32_e32 v85, v85, v239
	v_sub_f32_e32 v86, v86, v239
	v_sub_f32_e32 v87, v87, v239
	v_cndmask_b32_e64 v80, v238, v80, s[0:1]
	v_cndmask_b32_e64 v81, v238, v81, s[6:7]
	v_cndmask_b32_e64 v82, v238, v82, s[8:9]
	v_cndmask_b32_e64 v83, v238, v83, s[10:11]
	v_cndmask_b32_e64 v84, v238, v84, s[12:13]
	v_cndmask_b32_e64 v85, v238, v85, s[14:15]
	v_cndmask_b32_e64 v86, v238, v86, s[16:17]
	v_cndmask_b32_e64 v87, v238, v87, s[18:19]
	v_sub_f32_e32 v180, v180, v239
	v_sub_f32_e32 v181, v181, v239
	v_sub_f32_e32 v182, v182, v239
	v_sub_f32_e32 v183, v183, v239
	v_sub_f32_e32 v184, v184, v239
	v_sub_f32_e32 v185, v185, v239
	v_sub_f32_e32 v186, v186, v239
	v_sub_f32_e32 v187, v187, v239
	v_cndmask_b32_e64 v180, v238, v180, s[0:1]
	v_cndmask_b32_e64 v181, v238, v181, s[6:7]
	v_cndmask_b32_e64 v182, v238, v182, s[8:9]
	v_cndmask_b32_e64 v183, v238, v183, s[10:11]
	v_cndmask_b32_e64 v184, v238, v184, s[12:13]
	v_cndmask_b32_e64 v185, v238, v185, s[14:15]
	v_cndmask_b32_e64 v186, v238, v186, s[16:17]
	v_cndmask_b32_e64 v187, v238, v187, s[18:19]
	v_sub_f32_e32 v212, v212, v239
	v_sub_f32_e32 v213, v213, v239
	v_sub_f32_e32 v214, v214, v239
	v_sub_f32_e32 v215, v215, v239
	v_sub_f32_e32 v242, v242, v239
	v_sub_f32_e32 v243, v243, v239
	v_sub_f32_e32 v244, v244, v239
	v_sub_f32_e32 v245, v245, v239
	v_cndmask_b32_e64 v212, v238, v212, s[0:1]
	v_cndmask_b32_e64 v213, v238, v213, s[6:7]
	v_cndmask_b32_e64 v214, v238, v214, s[8:9]
	v_cndmask_b32_e64 v215, v238, v215, s[10:11]
	v_cndmask_b32_e64 v242, v238, v242, s[12:13]
	v_cndmask_b32_e64 v243, v238, v243, s[14:15]
	v_cndmask_b32_e64 v244, v238, v244, s[16:17]
	v_cndmask_b32_e64 v245, v238, v245, s[18:19]
	v_add_u32_e32 v240, 0x400, v240
	s_mov_b32 s92, -1
	s_mov_b32 s63, 2
	s_add_u32 s92, s92, 1
	s_add_u32 s63, s63, 1
	s_cmp_eq_u32 s63, 3
	s_cselect_b32 s63, 0, s63
	s_lshl_b32 s95, s63, 14
	s_lshr_b32 s20, s63, 1
	s_lshl_b32 s20, s20, 4
	s_add_u32 s95, s95, s20
	s_add_u32 s95, s95, 0x18000
	s_sub_i32 s80, s92, s60
	s_sub_i32 s89, s92, s76
	s_cmp_lt_i32 s80, 0
	s_cselect_b32 s89, s92, s89
	s_max_i32 s89, s89, 0
	s_min_i32 s89, s89, 7
	s_lshr_b32 s81, s89, 1
	s_lshl_b32 s81, s81, 14
	s_add_u32 s81, s81, 0x8000
	s_and_b32 s82, s89, 1
	s_lshl_b32 s20, s82, 8
	s_add_u32 s23, s81, s20
	s_lshl_b32 s20, s82, 10
	s_add_u32 s33, s81, s20
	s_add_u32 s33, s33, 0x2000
	s_cmp_ge_i32 s80, 0
	s_cselect_b32 s20, 1, 0
	s_cmp_lt_i32 s80, s76
	s_cselect_b32 s20, s20, 0
	s_cmp_lg_u32 s20, 0
	s_cbranch_scc0 .Latt_cs2
	s_add_u32 s23, s95, s97
	s_add_u32 s33, s95, s90
.Latt_cs2:
	s_waitcnt vmcnt(0) lgkmcnt(0)
	s_barrier
	v_add_u32_e32 v251, s23, v233
	v_add_u32_e32 v253, s33, v234
	ds_read_b128 v[176:179], v251 offset:0
	ds_read_b128 v[168:171], v251 offset:4096
	ds_read_b128 v[172:175], v251 offset:2048
	ds_read_b128 v[164:167], v251 offset:6144
	ds_read_b128 v[32:35], v253 offset:0
	ds_read_b128 v[28:31], v253 offset:2048
	ds_read_b128 v[24:27], v253 offset:4096
	ds_read_b128 v[20:23], v253 offset:6144
	s_mov_b32 s85, 0
	s_cmp_eq_u32 s60, 0
	s_cbranch_scc1 .Latt_went
	s_mov_b32 s85, 1
	s_mov_b32 s91, 4
	s_branch .Latt_CA
.Latt_went:
	s_mov_b32 s85, 0
	s_cmp_eq_u32 s76, 8
	s_cbranch_scc1 .Latt_n8
	s_add_u32 s21, s92, 3
	s_cmp_lt_u32 s21, s88
	s_cselect_b32 s87, 1, 0
	s_add_u32 s21, s21, s93
	s_lshl_b32 s22, s21, 7
	s_add_u32 s22, s22, s62
	s_lshl_b32 s21, s21, 16
	s_add_u32 s21, s21, s61
	s_add_u32 s84, s95, s94
	s_add_u32 s92, s92, 1
	s_add_u32 s63, s63, 1
	s_cmp_eq_u32 s63, 3
	s_cselect_b32 s63, 0, s63
	s_lshl_b32 s95, s63, 14
	s_lshr_b32 s20, s63, 1
	s_lshl_b32 s20, s20, 4
	s_add_u32 s95, s95, s20
	s_add_u32 s95, s95, 0x18000
	s_sub_i32 s80, s92, s60
	s_sub_i32 s89, s92, s76
	s_cmp_lt_i32 s80, 0
	s_cselect_b32 s89, s92, s89
	s_max_i32 s89, s89, 0
	s_min_i32 s89, s89, 7
	s_lshr_b32 s81, s89, 1
	s_lshl_b32 s81, s81, 14
	s_add_u32 s81, s81, 0x8000
	s_and_b32 s82, s89, 1
	s_lshl_b32 s20, s82, 8
	s_add_u32 s23, s81, s20
	s_lshl_b32 s20, s82, 10
	s_add_u32 s33, s81, s20
	s_add_u32 s33, s33, 0x2000
	s_cmp_ge_i32 s80, 0
	s_cselect_b32 s20, 1, 0
	s_cmp_lt_i32 s80, s76
	s_cselect_b32 s20, s20, 0
	s_cmp_lg_u32 s20, 0
	s_cbranch_scc0 .Latt_cs4
	s_add_u32 s23, s95, s97
	s_add_u32 s33, s95, s90
.Latt_cs4:
	s_waitcnt lgkmcnt(0)
	s_waitcnt vmcnt(2)
	s_cmp_lt_u32 s92, s88
	s_cbranch_scc0 .Latt_sk3b
	s_barrier
.Latt_sk3b:
	s_cmp_lg_u32 s87, 0
	s_cbranch_scc0 .Latt_sk3
	s_mov_b32 m0, s84
	s_add_u32 s84, s84, 0x2000
	buffer_load_dwordx4 v241, s[24:27], s21 offen lds
	s_mov_b32 m0, s84
	s_nop 0
	buffer_load_dwordx4 v255, s[40:43], s22 offen lds
.Latt_sk3:
	v_add_u32_e32 v251, s23, v233
	v_add_u32_e32 v253, s33, v234
	ds_read_b128 v[48:51], v251 offset:0
	ds_read_b128 v[40:43], v251 offset:4096
	ds_read_b128 v[44:47], v251 offset:2048
	ds_read_b128 v[36:39], v251 offset:6144
	ds_read_b128 v[16:19], v253 offset:0
	ds_read_b128 v[12:15], v253 offset:2048
	ds_read_b128 v[8:11], v253 offset:4096
	ds_read_b128 v[4:7], v253 offset:6144
	ds_read2_b32 v[212:213], v240 offset0:0 offset1:1
	ds_read2_b32 v[214:215], v240 offset0:2 offset1:3
	ds_read2_b32 v[242:243], v240 offset0:4 offset1:5
	ds_read2_b32 v[244:245], v240 offset0:6 offset1:7
	v_mfma_f32_16x16x32_bf16 v[188:191], v[176:179], v[132:135], v[204:207]
	v_mfma_f32_16x16x32_bf16 v[192:195], v[168:171], v[132:135], v[208:211]
	v_mfma_f32_16x16x32_bf16 v[188:191], v[172:175], v[136:139], v[188:191]
	v_mfma_f32_16x16x32_bf16 v[192:195], v[164:167], v[136:139], v[192:195]
	s_nop 6
	v_exp_f32_e32 v188, v188
	v_exp_f32_e32 v189, v189
	v_exp_f32_e32 v190, v190
	v_exp_f32_e32 v191, v191
	v_exp_f32_e32 v192, v192
	v_exp_f32_e32 v193, v193
	v_exp_f32_e32 v194, v194
	v_exp_f32_e32 v195, v195
	v_cvt_pk_bf16_f32 v246, v188, v189
	v_cvt_pk_bf16_f32 v247, v190, v191
	v_cvt_pk_bf16_f32 v248, v192, v193
	v_cvt_pk_bf16_f32 v249, v194, v195
	v_add_f32_e32 v188, v188, v189
	v_add_f32_e32 v190, v190, v191
	v_add_f32_e32 v192, v192, v193
	v_add_f32_e32 v194, v194, v195
	v_add_f32_e32 v188, v188, v190
	v_add_f32_e32 v192, v192, v194
	v_add_f32_e32 v188, v188, v192
	v_add_f32_e32 v222, v222, v188
	s_waitcnt lgkmcnt(0)
	v_sub_f32_e32 v212, v212, v239
	v_sub_f32_e32 v213, v213, v239
	v_sub_f32_e32 v214, v214, v239
	v_mfma_f32_16x16x32_bf16 v[96:99], v[32:35], v[246:249], v[96:99]
	v_sub_f32_e32 v215, v215, v239
	v_sub_f32_e32 v242, v242, v239
	v_sub_f32_e32 v243, v243, v239
	v_mfma_f32_16x16x32_bf16 v[88:91], v[28:31], v[246:249], v[88:91]
	v_sub_f32_e32 v244, v244, v239
	v_sub_f32_e32 v245, v245, v239
	v_cndmask_b32_e64 v212, v238, v212, s[0:1]
	v_mfma_f32_16x16x32_bf16 v[72:75], v[24:27], v[246:249], v[72:75]
	v_cndmask_b32_e64 v213, v238, v213, s[6:7]
	v_cndmask_b32_e64 v214, v238, v214, s[8:9]
	v_cndmask_b32_e64 v215, v238, v215, s[10:11]
	v_mfma_f32_16x16x32_bf16 v[68:71], v[20:23], v[246:249], v[68:71]
	v_cndmask_b32_e64 v242, v238, v242, s[12:13]
	v_cndmask_b32_e64 v243, v238, v243, s[14:15]
	v_cndmask_b32_e64 v244, v238, v244, s[16:17]
	v_cndmask_b32_e64 v245, v238, v245, s[18:19]
	v_add_u32_e32 v240, 0x100, v240
	s_add_u32 s21, s92, 3
	s_cmp_lt_u32 s21, s88
	s_cselect_b32 s87, 1, 0
	s_add_u32 s21, s21, s93
	s_lshl_b32 s22, s21, 7
	s_add_u32 s22, s22, s62
	s_lshl_b32 s21, s21, 16
	s_add_u32 s21, s21, s61
	s_add_u32 s84, s95, s94
	s_add_u32 s92, s92, 1
	s_add_u32 s63, s63, 1
	s_cmp_eq_u32 s63, 3
	s_cselect_b32 s63, 0, s63
	s_lshl_b32 s95, s63, 14
	s_lshr_b32 s20, s63, 1
	s_lshl_b32 s20, s20, 4
	s_add_u32 s95, s95, s20
	s_add_u32 s95, s95, 0x18000
	s_sub_i32 s80, s92, s60
	s_sub_i32 s89, s92, s76
	s_cmp_lt_i32 s80, 0
	s_cselect_b32 s89, s92, s89
	s_max_i32 s89, s89, 0
	s_min_i32 s89, s89, 7
	s_lshr_b32 s81, s89, 1
	s_lshl_b32 s81, s81, 14
	s_add_u32 s81, s81, 0x8000
	s_and_b32 s82, s89, 1
	s_lshl_b32 s20, s82, 8
	s_add_u32 s23, s81, s20
	s_lshl_b32 s20, s82, 10
	s_add_u32 s33, s81, s20
	s_add_u32 s33, s33, 0x2000
	s_cmp_ge_i32 s80, 0
	s_cselect_b32 s20, 1, 0
	s_cmp_lt_i32 s80, s76
	s_cselect_b32 s20, s20, 0
	s_cmp_lg_u32 s20, 0
	s_cbranch_scc0 .Latt_cs6
	s_add_u32 s23, s95, s97
	s_add_u32 s33, s95, s90

.Latt_sk5:
	v_add_u32_e32 v251, s23, v233
	v_add_u32_e32 v253, s33, v234
	ds_read_b128 v[176:179], v251 offset:0
	ds_read_b128 v[168:171], v251 offset:4096
	ds_read_b128 v[172:175], v251 offset:2048
	ds_read_b128 v[164:167], v251 offset:6144
	ds_read_b128 v[32:35], v253 offset:0
	ds_read_b128 v[28:31], v253 offset:2048
	ds_read_b128 v[24:27], v253 offset:4096
	ds_read_b128 v[20:23], v253 offset:6144
	ds_read2_b32 v[180:181], v240 offset0:0 offset1:1
	ds_read2_b32 v[182:183], v240 offset0:2 offset1:3
	ds_read2_b32 v[184:185], v240 offset0:4 offset1:5
	ds_read2_b32 v[186:187], v240 offset0:6 offset1:7
	v_mfma_f32_16x16x32_bf16 v[188:191], v[48:51], v[140:143], v[204:207]
	v_mfma_f32_16x16x32_bf16 v[192:195], v[40:43], v[140:143], v[208:211]
	v_mfma_f32_16x16x32_bf16 v[188:191], v[44:47], v[144:147], v[188:191]
	v_mfma_f32_16x16x32_bf16 v[192:195], v[36:39], v[144:147], v[192:195]
	v_mfma_f32_16x16x32_bf16 v[196:199], v[48:51], v[132:135], v[212:215]
	v_mfma_f32_16x16x32_bf16 v[200:203], v[40:43], v[132:135], v[242:245]
	v_mfma_f32_16x16x32_bf16 v[196:199], v[44:47], v[136:139], v[196:199]
	v_mfma_f32_16x16x32_bf16 v[200:203], v[36:39], v[136:139], v[200:203]
	s_nop 2
	v_exp_f32_e32 v188, v188
	v_exp_f32_e32 v189, v189
	v_exp_f32_e32 v190, v190
	v_exp_f32_e32 v191, v191
	v_exp_f32_e32 v192, v192
	v_exp_f32_e32 v193, v193
	v_exp_f32_e32 v194, v194
	v_exp_f32_e32 v195, v195
	v_cvt_pk_bf16_f32 v246, v188, v189
	v_cvt_pk_bf16_f32 v247, v190, v191
	v_cvt_pk_bf16_f32 v248, v192, v193
	v_cvt_pk_bf16_f32 v249, v194, v195
	v_add_f32_e32 v188, v188, v189
	v_add_f32_e32 v190, v190, v191
	v_add_f32_e32 v192, v192, v193
	v_add_f32_e32 v194, v194, v195
	v_add_f32_e32 v188, v188, v190
	v_add_f32_e32 v192, v192, v194
	v_add_f32_e32 v188, v188, v192
	v_add_f32_e32 v223, v223, v188
	v_exp_f32_e32 v196, v196
	v_exp_f32_e32 v197, v197
	v_exp_f32_e32 v198, v198
	v_exp_f32_e32 v199, v199
	v_mfma_f32_16x16x32_bf16 v[64:67], v[16:19], v[246:249], v[64:67]
	v_exp_f32_e32 v200, v200
	v_exp_f32_e32 v201, v201
	v_exp_f32_e32 v202, v202
	v_exp_f32_e32 v203, v203
	v_mfma_f32_16x16x32_bf16 v[60:63], v[12:15], v[246:249], v[60:63]
	v_cvt_pk_bf16_f32 v92, v196, v197
	v_cvt_pk_bf16_f32 v93, v198, v199
	v_cvt_pk_bf16_f32 v94, v200, v201
	v_cvt_pk_bf16_f32 v95, v202, v203
	v_mfma_f32_16x16x32_bf16 v[56:59], v[8:11], v[246:249], v[56:59]
	v_add_f32_e32 v196, v196, v197
	v_add_f32_e32 v198, v198, v199
	v_add_f32_e32 v200, v200, v201
	v_add_f32_e32 v202, v202, v203
	v_mfma_f32_16x16x32_bf16 v[52:55], v[4:7], v[246:249], v[52:55]
	v_add_f32_e32 v196, v196, v198
	v_add_f32_e32 v200, v200, v202
	v_add_f32_e32 v196, v196, v200
	v_add_f32_e32 v222, v222, v196
	s_waitcnt lgkmcnt(0)
	v_sub_f32_e32 v180, v180, v239
	v_sub_f32_e32 v181, v181, v239
	v_sub_f32_e32 v182, v182, v239
	v_mfma_f32_16x16x32_bf16 v[96:99], v[16:19], v[92:95], v[96:99]
	v_sub_f32_e32 v183, v183, v239
	v_sub_f32_e32 v184, v184, v239
	v_sub_f32_e32 v185, v185, v239
	v_mfma_f32_16x16x32_bf16 v[88:91], v[12:15], v[92:95], v[88:91]
	v_sub_f32_e32 v186, v186, v239
	v_sub_f32_e32 v187, v187, v239
	v_cndmask_b32_e64 v180, v238, v180, s[0:1]
	v_mfma_f32_16x16x32_bf16 v[72:75], v[8:11], v[92:95], v[72:75]
	v_cndmask_b32_e64 v181, v238, v181, s[6:7]
	v_cndmask_b32_e64 v182, v238, v182, s[8:9]
	v_cndmask_b32_e64 v183, v238, v183, s[10:11]
	v_mfma_f32_16x16x32_bf16 v[68:71], v[4:7], v[92:95], v[68:71]
	v_cndmask_b32_e64 v184, v238, v184, s[12:13]
	v_cndmask_b32_e64 v185, v238, v185, s[14:15]
	v_cndmask_b32_e64 v186, v238, v186, s[16:17]
	v_cndmask_b32_e64 v187, v238, v187, s[18:19]
	v_add_u32_e32 v240, 0x100, v240
	s_add_u32 s21, s92, 3
	s_cmp_lt_u32 s21, s88
	s_cselect_b32 s87, 1, 0
	s_add_u32 s21, s21, s93
	s_lshl_b32 s22, s21, 7
	s_add_u32 s22, s22, s62
	s_lshl_b32 s21, s21, 16
	s_add_u32 s21, s21, s61
	s_add_u32 s84, s95, s94
	s_add_u32 s92, s92, 1
	s_add_u32 s63, s63, 1
	s_cmp_eq_u32 s63, 3
	s_cselect_b32 s63, 0, s63
	s_lshl_b32 s95, s63, 14
	s_lshr_b32 s20, s63, 1
	s_lshl_b32 s20, s20, 4
	s_add_u32 s95, s95, s20
	s_add_u32 s95, s95, 0x18000
	s_sub_i32 s80, s92, s60
	s_sub_i32 s89, s92, s76
	s_cmp_lt_i32 s80, 0
	s_cselect_b32 s89, s92, s89
	s_max_i32 s89, s89, 0
	s_min_i32 s89, s89, 7
	s_lshr_b32 s81, s89, 1
	s_lshl_b32 s81, s81, 14
	s_add_u32 s81, s81, 0x8000
	s_and_b32 s82, s89, 1
	s_lshl_b32 s20, s82, 8
	s_add_u32 s23, s81, s20
	s_lshl_b32 s20, s82, 10
	s_add_u32 s33, s81, s20
	s_add_u32 s33, s33, 0x2000
	s_cmp_ge_i32 s80, 0
	s_cselect_b32 s20, 1, 0
	s_cmp_lt_i32 s80, s76
	s_cselect_b32 s20, s20, 0
	s_cmp_lg_u32 s20, 0
	s_cbranch_scc0 .Latt_cs8
	s_add_u32 s23, s95, s97
	s_add_u32 s33, s95, s90

.Latt_sk7:
	v_add_u32_e32 v251, s23, v233
	v_add_u32_e32 v253, s33, v234
	ds_read_b128 v[48:51], v251 offset:0
	ds_read_b128 v[40:43], v251 offset:4096
	ds_read_b128 v[44:47], v251 offset:2048
	ds_read_b128 v[36:39], v251 offset:6144
	ds_read_b128 v[16:19], v253 offset:0
	ds_read_b128 v[12:15], v253 offset:2048
	ds_read_b128 v[8:11], v253 offset:4096
	ds_read_b128 v[4:7], v253 offset:6144
	ds_read2_b32 v[80:81], v240 offset0:0 offset1:1
	ds_read2_b32 v[82:83], v240 offset0:2 offset1:3
	ds_read2_b32 v[84:85], v240 offset0:4 offset1:5
	ds_read2_b32 v[86:87], v240 offset0:6 offset1:7
	v_mfma_f32_16x16x32_bf16 v[188:191], v[176:179], v[148:151], v[204:207]
	v_mfma_f32_16x16x32_bf16 v[192:195], v[168:171], v[148:151], v[208:211]
	v_mfma_f32_16x16x32_bf16 v[188:191], v[172:175], v[152:155], v[188:191]
	v_mfma_f32_16x16x32_bf16 v[192:195], v[164:167], v[152:155], v[192:195]
	v_mfma_f32_16x16x32_bf16 v[196:199], v[176:179], v[140:143], v[212:215]
	v_mfma_f32_16x16x32_bf16 v[200:203], v[168:171], v[140:143], v[242:245]
	v_mfma_f32_16x16x32_bf16 v[196:199], v[172:175], v[144:147], v[196:199]
	v_mfma_f32_16x16x32_bf16 v[200:203], v[164:167], v[144:147], v[200:203]
	s_nop 2
	v_exp_f32_e32 v188, v188
	v_exp_f32_e32 v189, v189
	v_exp_f32_e32 v190, v190
	v_exp_f32_e32 v191, v191
	v_exp_f32_e32 v192, v192
	v_exp_f32_e32 v193, v193
	v_exp_f32_e32 v194, v194
	v_exp_f32_e32 v195, v195
	v_cvt_pk_bf16_f32 v246, v188, v189
	v_cvt_pk_bf16_f32 v247, v190, v191
	v_cvt_pk_bf16_f32 v248, v192, v193
	v_cvt_pk_bf16_f32 v249, v194, v195
	v_add_f32_e32 v188, v188, v189
	v_add_f32_e32 v190, v190, v191
	v_add_f32_e32 v192, v192, v193
	v_add_f32_e32 v194, v194, v195
	v_add_f32_e32 v188, v188, v190
	v_add_f32_e32 v192, v192, v194
	v_add_f32_e32 v188, v188, v192
	v_add_f32_e32 v224, v224, v188
	v_mfma_f32_16x16x32_bf16 v[188:191], v[176:179], v[132:135], v[180:183]
	v_mfma_f32_16x16x32_bf16 v[192:195], v[168:171], v[132:135], v[184:187]
	v_mfma_f32_16x16x32_bf16 v[188:191], v[172:175], v[136:139], v[188:191]
	v_mfma_f32_16x16x32_bf16 v[192:195], v[164:167], v[136:139], v[192:195]
	v_exp_f32_e32 v196, v196
	v_exp_f32_e32 v197, v197
	v_exp_f32_e32 v198, v198
	v_exp_f32_e32 v199, v199
	v_mfma_f32_16x16x32_bf16 v[128:131], v[32:35], v[246:249], v[128:131]
	v_exp_f32_e32 v200, v200
	v_exp_f32_e32 v201, v201
	v_exp_f32_e32 v202, v202
	v_exp_f32_e32 v203, v203
	v_mfma_f32_16x16x32_bf16 v[124:127], v[28:31], v[246:249], v[124:127]
	v_cvt_pk_bf16_f32 v92, v196, v197
	v_cvt_pk_bf16_f32 v93, v198, v199
	v_cvt_pk_bf16_f32 v94, v200, v201
	v_cvt_pk_bf16_f32 v95, v202, v203
	v_mfma_f32_16x16x32_bf16 v[120:123], v[24:27], v[246:249], v[120:123]
	v_add_f32_e32 v196, v196, v197
	v_add_f32_e32 v198, v198, v199
	v_add_f32_e32 v200, v200, v201
	v_add_f32_e32 v202, v202, v203
	v_mfma_f32_16x16x32_bf16 v[116:119], v[20:23], v[246:249], v[116:119]
	v_add_f32_e32 v196, v196, v198
	v_add_f32_e32 v200, v200, v202
	v_add_f32_e32 v196, v196, v200
	v_add_f32_e32 v223, v223, v196
	v_exp_f32_e32 v188, v188
	v_exp_f32_e32 v189, v189
	v_exp_f32_e32 v190, v190
	v_exp_f32_e32 v191, v191
	v_mfma_f32_16x16x32_bf16 v[64:67], v[32:35], v[92:95], v[64:67]
	v_exp_f32_e32 v192, v192
	v_exp_f32_e32 v193, v193
	v_exp_f32_e32 v194, v194
	v_exp_f32_e32 v195, v195
	v_mfma_f32_16x16x32_bf16 v[60:63], v[28:31], v[92:95], v[60:63]
	v_cvt_pk_bf16_f32 v246, v188, v189
	v_cvt_pk_bf16_f32 v247, v190, v191
	v_cvt_pk_bf16_f32 v248, v192, v193
	v_cvt_pk_bf16_f32 v249, v194, v195
	v_mfma_f32_16x16x32_bf16 v[56:59], v[24:27], v[92:95], v[56:59]
	v_add_f32_e32 v188, v188, v189
	v_add_f32_e32 v190, v190, v191
	v_add_f32_e32 v192, v192, v193
	v_add_f32_e32 v194, v194, v195
	v_mfma_f32_16x16x32_bf16 v[52:55], v[20:23], v[92:95], v[52:55]
	v_add_f32_e32 v188, v188, v190
	v_add_f32_e32 v192, v192, v194
	v_add_f32_e32 v188, v188, v192
	v_add_f32_e32 v222, v222, v188
	s_waitcnt lgkmcnt(0)
	v_sub_f32_e32 v80, v80, v239
	v_sub_f32_e32 v81, v81, v239
	v_sub_f32_e32 v82, v82, v239
	v_mfma_f32_16x16x32_bf16 v[96:99], v[32:35], v[246:249], v[96:99]
	v_sub_f32_e32 v83, v83, v239
	v_sub_f32_e32 v84, v84, v239
	v_sub_f32_e32 v85, v85, v239
	v_mfma_f32_16x16x32_bf16 v[88:91], v[28:31], v[246:249], v[88:91]
	v_sub_f32_e32 v86, v86, v239
	v_sub_f32_e32 v87, v87, v239
	v_cndmask_b32_e64 v80, v238, v80, s[0:1]
	v_mfma_f32_16x16x32_bf16 v[72:75], v[24:27], v[246:249], v[72:75]
	v_cndmask_b32_e64 v81, v238, v81, s[6:7]
	v_cndmask_b32_e64 v82, v238, v82, s[8:9]
	v_cndmask_b32_e64 v83, v238, v83, s[10:11]
	v_mfma_f32_16x16x32_bf16 v[68:71], v[20:23], v[246:249], v[68:71]
	v_cndmask_b32_e64 v84, v238, v84, s[12:13]
	v_cndmask_b32_e64 v85, v238, v85, s[14:15]
	v_cndmask_b32_e64 v86, v238, v86, s[16:17]
	v_cndmask_b32_e64 v87, v238, v87, s[18:19]
	v_add_u32_e32 v240, 0x100, v240
	s_add_u32 s21, s92, 3
	s_cmp_lt_u32 s21, s88
	s_cselect_b32 s87, 1, 0
	s_add_u32 s21, s21, s93
	s_lshl_b32 s22, s21, 7
	s_add_u32 s22, s22, s62
	s_lshl_b32 s21, s21, 16
	s_add_u32 s21, s21, s61
	s_add_u32 s84, s95, s94
	s_add_u32 s92, s92, 1
	s_add_u32 s63, s63, 1
	s_cmp_eq_u32 s63, 3
	s_cselect_b32 s63, 0, s63
	s_lshl_b32 s95, s63, 14
	s_lshr_b32 s20, s63, 1
	s_lshl_b32 s20, s20, 4
	s_add_u32 s95, s95, s20
	s_add_u32 s95, s95, 0x18000
	s_sub_i32 s80, s92, s60
	s_sub_i32 s89, s92, s76
	s_cmp_lt_i32 s80, 0
	s_cselect_b32 s89, s92, s89
	s_max_i32 s89, s89, 0
	s_min_i32 s89, s89, 7
	s_lshr_b32 s81, s89, 1
	s_lshl_b32 s81, s81, 14
	s_add_u32 s81, s81, 0x8000
	s_and_b32 s82, s89, 1
	s_lshl_b32 s20, s82, 8
	s_add_u32 s23, s81, s20
	s_lshl_b32 s20, s82, 10
	s_add_u32 s33, s81, s20
	s_add_u32 s33, s33, 0x2000
	s_cmp_ge_i32 s80, 0
	s_cselect_b32 s20, 1, 0
	s_cmp_lt_i32 s80, s76
	s_cselect_b32 s20, s20, 0
	s_cmp_lg_u32 s20, 0
	s_cbranch_scc0 .Latt_cs10
	s_add_u32 s23, s95, s97
	s_add_u32 s33, s95, s90

.Latt_sk9:
	v_add_u32_e32 v251, s23, v233
	v_add_u32_e32 v253, s33, v234
	ds_read_b128 v[176:179], v251 offset:0
	ds_read_b128 v[168:171], v251 offset:4096
	ds_read_b128 v[172:175], v251 offset:2048
	ds_read_b128 v[164:167], v251 offset:6144
	ds_read_b128 v[32:35], v253 offset:0
	ds_read_b128 v[28:31], v253 offset:2048
	ds_read_b128 v[24:27], v253 offset:4096
	ds_read_b128 v[20:23], v253 offset:6144
	v_mfma_f32_16x16x32_bf16 v[188:191], v[48:51], v[156:159], v[204:207]
	v_mfma_f32_16x16x32_bf16 v[192:195], v[40:43], v[156:159], v[208:211]
	v_mfma_f32_16x16x32_bf16 v[188:191], v[44:47], v[160:163], v[188:191]
	v_mfma_f32_16x16x32_bf16 v[192:195], v[36:39], v[160:163], v[192:195]
	ds_read2_b32 v[204:205], v240 offset0:0 offset1:1
	ds_read2_b32 v[206:207], v240 offset0:2 offset1:3
	ds_read2_b32 v[208:209], v240 offset0:4 offset1:5
	ds_read2_b32 v[210:211], v240 offset0:6 offset1:7
	v_mfma_f32_16x16x32_bf16 v[196:199], v[48:51], v[148:151], v[212:215]
	v_mfma_f32_16x16x32_bf16 v[200:203], v[40:43], v[148:151], v[242:245]
	v_mfma_f32_16x16x32_bf16 v[196:199], v[44:47], v[152:155], v[196:199]
	v_mfma_f32_16x16x32_bf16 v[200:203], v[36:39], v[152:155], v[200:203]
	v_exp_f32_e32 v188, v188
	v_exp_f32_e32 v189, v189
	v_exp_f32_e32 v190, v190
	v_exp_f32_e32 v191, v191
	v_exp_f32_e32 v192, v192
	v_exp_f32_e32 v193, v193
	v_exp_f32_e32 v194, v194
	v_exp_f32_e32 v195, v195
	v_cvt_pk_bf16_f32 v246, v188, v189
	v_cvt_pk_bf16_f32 v247, v190, v191
	v_cvt_pk_bf16_f32 v248, v192, v193
	v_cvt_pk_bf16_f32 v249, v194, v195
	v_add_f32_e32 v188, v188, v189
	v_add_f32_e32 v190, v190, v191
	v_add_f32_e32 v192, v192, v193
	v_add_f32_e32 v194, v194, v195
	v_add_f32_e32 v188, v188, v190
	v_add_f32_e32 v192, v192, v194
	v_add_f32_e32 v188, v188, v192
	v_add_f32_e32 v225, v225, v188
	v_mfma_f32_16x16x32_bf16 v[188:191], v[48:51], v[140:143], v[180:183]
	v_mfma_f32_16x16x32_bf16 v[192:195], v[40:43], v[140:143], v[184:187]
	v_mfma_f32_16x16x32_bf16 v[188:191], v[44:47], v[144:147], v[188:191]
	v_mfma_f32_16x16x32_bf16 v[192:195], v[36:39], v[144:147], v[192:195]
	v_exp_f32_e32 v196, v196
	v_exp_f32_e32 v197, v197
	v_exp_f32_e32 v198, v198
	v_exp_f32_e32 v199, v199
	v_mfma_f32_16x16x32_bf16 v[112:115], v[16:19], v[246:249], v[112:115]
	v_exp_f32_e32 v200, v200
	v_exp_f32_e32 v201, v201
	v_exp_f32_e32 v202, v202
	v_exp_f32_e32 v203, v203
	v_mfma_f32_16x16x32_bf16 v[108:111], v[12:15], v[246:249], v[108:111]
	v_cvt_pk_bf16_f32 v92, v196, v197
	v_cvt_pk_bf16_f32 v93, v198, v199
	v_cvt_pk_bf16_f32 v94, v200, v201
	v_cvt_pk_bf16_f32 v95, v202, v203
	v_mfma_f32_16x16x32_bf16 v[104:107], v[8:11], v[246:249], v[104:107]
	v_add_f32_e32 v196, v196, v197
	v_add_f32_e32 v198, v198, v199
	v_add_f32_e32 v200, v200, v201
	v_add_f32_e32 v202, v202, v203
	v_mfma_f32_16x16x32_bf16 v[100:103], v[4:7], v[246:249], v[100:103]
	v_add_f32_e32 v196, v196, v198
	v_add_f32_e32 v200, v200, v202
	v_add_f32_e32 v196, v196, v200
	v_add_f32_e32 v224, v224, v196
	v_mfma_f32_16x16x32_bf16 v[196:199], v[48:51], v[132:135], v[80:83]
	v_mfma_f32_16x16x32_bf16 v[200:203], v[40:43], v[132:135], v[84:87]
	v_mfma_f32_16x16x32_bf16 v[196:199], v[44:47], v[136:139], v[196:199]
	v_mfma_f32_16x16x32_bf16 v[200:203], v[36:39], v[136:139], v[200:203]
	v_exp_f32_e32 v188, v188
	v_exp_f32_e32 v189, v189
	v_exp_f32_e32 v190, v190
	v_exp_f32_e32 v191, v191
	v_mfma_f32_16x16x32_bf16 v[128:131], v[16:19], v[92:95], v[128:131]
	v_exp_f32_e32 v192, v192
	v_exp_f32_e32 v193, v193
	v_exp_f32_e32 v194, v194
	v_exp_f32_e32 v195, v195
	v_mfma_f32_16x16x32_bf16 v[124:127], v[12:15], v[92:95], v[124:127]
	v_cvt_pk_bf16_f32 v246, v188, v189
	v_cvt_pk_bf16_f32 v247, v190, v191
	v_cvt_pk_bf16_f32 v248, v192, v193
	v_cvt_pk_bf16_f32 v249, v194, v195
	v_mfma_f32_16x16x32_bf16 v[120:123], v[8:11], v[92:95], v[120:123]
	v_add_f32_e32 v188, v188, v189
	v_add_f32_e32 v190, v190, v191
	v_add_f32_e32 v192, v192, v193
	v_add_f32_e32 v194, v194, v195
	v_mfma_f32_16x16x32_bf16 v[116:119], v[4:7], v[92:95], v[116:119]
	v_add_f32_e32 v188, v188, v190
	v_add_f32_e32 v192, v192, v194
	v_add_f32_e32 v188, v188, v192
	v_add_f32_e32 v223, v223, v188
	v_exp_f32_e32 v196, v196
	v_exp_f32_e32 v197, v197
	v_exp_f32_e32 v198, v198
	v_exp_f32_e32 v199, v199
	v_mfma_f32_16x16x32_bf16 v[64:67], v[16:19], v[246:249], v[64:67]
	v_exp_f32_e32 v200, v200
	v_exp_f32_e32 v201, v201
	v_exp_f32_e32 v202, v202
	v_exp_f32_e32 v203, v203
	v_mfma_f32_16x16x32_bf16 v[60:63], v[12:15], v[246:249], v[60:63]
	v_cvt_pk_bf16_f32 v92, v196, v197
	v_cvt_pk_bf16_f32 v93, v198, v199
	v_cvt_pk_bf16_f32 v94, v200, v201
	v_cvt_pk_bf16_f32 v95, v202, v203
	v_mfma_f32_16x16x32_bf16 v[56:59], v[8:11], v[246:249], v[56:59]
	v_add_f32_e32 v196, v196, v197
	v_add_f32_e32 v198, v198, v199
	v_add_f32_e32 v200, v200, v201
	v_add_f32_e32 v202, v202, v203
	v_mfma_f32_16x16x32_bf16 v[52:55], v[4:7], v[246:249], v[52:55]
	v_add_f32_e32 v196, v196, v198
	v_add_f32_e32 v200, v200, v202
	v_add_f32_e32 v196, v196, v200
	v_add_f32_e32 v222, v222, v196
	s_waitcnt lgkmcnt(0)
	v_sub_f32_e32 v204, v204, v239
	v_sub_f32_e32 v205, v205, v239
	v_sub_f32_e32 v206, v206, v239
	v_mfma_f32_16x16x32_bf16 v[96:99], v[16:19], v[92:95], v[96:99]
	v_sub_f32_e32 v207, v207, v239
	v_sub_f32_e32 v208, v208, v239
	v_sub_f32_e32 v209, v209, v239
	v_mfma_f32_16x16x32_bf16 v[88:91], v[12:15], v[92:95], v[88:91]
	v_sub_f32_e32 v210, v210, v239
	v_sub_f32_e32 v211, v211, v239
	v_cndmask_b32_e64 v204, v238, v204, s[0:1]
	v_mfma_f32_16x16x32_bf16 v[72:75], v[8:11], v[92:95], v[72:75]
	v_cndmask_b32_e64 v205, v238, v205, s[6:7]
	v_cndmask_b32_e64 v206, v238, v206, s[8:9]
	v_cndmask_b32_e64 v207, v238, v207, s[10:11]
	v_mfma_f32_16x16x32_bf16 v[68:71], v[4:7], v[92:95], v[68:71]
	v_cndmask_b32_e64 v208, v238, v208, s[12:13]
	v_cndmask_b32_e64 v209, v238, v209, s[14:15]
	v_cndmask_b32_e64 v210, v238, v210, s[16:17]
	v_cndmask_b32_e64 v211, v238, v211, s[18:19]
	v_add_u32_e32 v240, 0x100, v240
	s_add_u32 s21, s92, 3
	s_cmp_lt_u32 s21, s88
	s_cselect_b32 s87, 1, 0
	s_add_u32 s21, s21, s93
	s_lshl_b32 s22, s21, 7
	s_add_u32 s22, s22, s62
	s_lshl_b32 s21, s21, 16
	s_add_u32 s21, s21, s61
	s_add_u32 s84, s95, s94
	s_add_u32 s92, s92, 1
	s_add_u32 s63, s63, 1
	s_cmp_eq_u32 s63, 3
	s_cselect_b32 s63, 0, s63
	s_lshl_b32 s95, s63, 14
	s_lshr_b32 s20, s63, 1
	s_lshl_b32 s20, s20, 4
	s_add_u32 s95, s95, s20
	s_add_u32 s95, s95, 0x18000
	s_sub_i32 s80, s92, s60
	s_sub_i32 s89, s92, s76
	s_cmp_lt_i32 s80, 0
	s_cselect_b32 s89, s92, s89
	s_max_i32 s89, s89, 0
	s_min_i32 s89, s89, 7
	s_lshr_b32 s81, s89, 1
	s_lshl_b32 s81, s81, 14
	s_add_u32 s81, s81, 0x8000
	s_and_b32 s82, s89, 1
	s_lshl_b32 s20, s82, 8
	s_add_u32 s23, s81, s20
	s_lshl_b32 s20, s82, 10
	s_add_u32 s33, s81, s20
	s_add_u32 s33, s33, 0x2000
	s_cmp_ge_i32 s80, 0
	s_cselect_b32 s20, 1, 0
	s_cmp_lt_i32 s80, s76
	s_cselect_b32 s20, s20, 0
	s_cmp_lg_u32 s20, 0
	s_cbranch_scc0 .Latt_cs12
	s_add_u32 s23, s95, s97
	s_add_u32 s33, s95, s90

.Latt_sk11:
	v_add_u32_e32 v251, s23, v233
	v_add_u32_e32 v253, s33, v234
	ds_read_b128 v[48:51], v251 offset:0
	ds_read_b128 v[40:43], v251 offset:4096
	ds_read_b128 v[44:47], v251 offset:2048
	ds_read_b128 v[36:39], v251 offset:6144
	ds_read_b128 v[16:19], v253 offset:0
	ds_read_b128 v[12:15], v253 offset:2048
	ds_read_b128 v[8:11], v253 offset:4096
	ds_read_b128 v[4:7], v253 offset:6144
	v_mfma_f32_16x16x32_bf16 v[188:191], v[176:179], v[156:159], v[212:215]
	v_mfma_f32_16x16x32_bf16 v[192:195], v[168:171], v[156:159], v[242:245]
	v_mfma_f32_16x16x32_bf16 v[188:191], v[172:175], v[160:163], v[188:191]
	v_mfma_f32_16x16x32_bf16 v[192:195], v[164:167], v[160:163], v[192:195]
	ds_read2_b32 v[212:213], v240 offset0:0 offset1:1
	ds_read2_b32 v[214:215], v240 offset0:2 offset1:3
	ds_read2_b32 v[242:243], v240 offset0:4 offset1:5
	ds_read2_b32 v[244:245], v240 offset0:6 offset1:7
	v_mfma_f32_16x16x32_bf16 v[196:199], v[176:179], v[148:151], v[180:183]
	v_mfma_f32_16x16x32_bf16 v[200:203], v[168:171], v[148:151], v[184:187]
	v_mfma_f32_16x16x32_bf16 v[196:199], v[172:175], v[152:155], v[196:199]
	v_mfma_f32_16x16x32_bf16 v[200:203], v[164:167], v[152:155], v[200:203]
	v_exp_f32_e32 v188, v188
	v_exp_f32_e32 v189, v189
	v_exp_f32_e32 v190, v190
	v_exp_f32_e32 v191, v191
	v_exp_f32_e32 v192, v192
	v_exp_f32_e32 v193, v193
	v_exp_f32_e32 v194, v194
	v_exp_f32_e32 v195, v195
	v_cvt_pk_bf16_f32 v246, v188, v189
	v_cvt_pk_bf16_f32 v247, v190, v191
	v_cvt_pk_bf16_f32 v248, v192, v193
	v_cvt_pk_bf16_f32 v249, v194, v195
	v_add_f32_e32 v188, v188, v189
	v_add_f32_e32 v190, v190, v191
	v_add_f32_e32 v192, v192, v193
	v_add_f32_e32 v194, v194, v195
	v_add_f32_e32 v188, v188, v190
	v_add_f32_e32 v192, v192, v194
	v_add_f32_e32 v188, v188, v192
	v_add_f32_e32 v225, v225, v188
	v_mfma_f32_16x16x32_bf16 v[188:191], v[176:179], v[140:143], v[80:83]
	v_mfma_f32_16x16x32_bf16 v[192:195], v[168:171], v[140:143], v[84:87]
	v_mfma_f32_16x16x32_bf16 v[188:191], v[172:175], v[144:147], v[188:191]
	v_mfma_f32_16x16x32_bf16 v[192:195], v[164:167], v[144:147], v[192:195]
	v_exp_f32_e32 v196, v196
	v_exp_f32_e32 v197, v197
	v_exp_f32_e32 v198, v198
	v_exp_f32_e32 v199, v199
	v_mfma_f32_16x16x32_bf16 v[112:115], v[32:35], v[246:249], v[112:115]
	v_exp_f32_e32 v200, v200
	v_exp_f32_e32 v201, v201
	v_exp_f32_e32 v202, v202
	v_exp_f32_e32 v203, v203
	v_mfma_f32_16x16x32_bf16 v[108:111], v[28:31], v[246:249], v[108:111]
	v_cvt_pk_bf16_f32 v92, v196, v197
	v_cvt_pk_bf16_f32 v93, v198, v199
	v_cvt_pk_bf16_f32 v94, v200, v201
	v_cvt_pk_bf16_f32 v95, v202, v203
	v_mfma_f32_16x16x32_bf16 v[104:107], v[24:27], v[246:249], v[104:107]
	v_add_f32_e32 v196, v196, v197
	v_add_f32_e32 v198, v198, v199
	v_add_f32_e32 v200, v200, v201
	v_add_f32_e32 v202, v202, v203
	v_mfma_f32_16x16x32_bf16 v[100:103], v[20:23], v[246:249], v[100:103]
	v_add_f32_e32 v196, v196, v198
	v_add_f32_e32 v200, v200, v202
	v_add_f32_e32 v196, v196, v200
	v_add_f32_e32 v224, v224, v196
	v_mfma_f32_16x16x32_bf16 v[196:199], v[176:179], v[132:135], v[204:207]
	v_mfma_f32_16x16x32_bf16 v[200:203], v[168:171], v[132:135], v[208:211]
	v_mfma_f32_16x16x32_bf16 v[196:199], v[172:175], v[136:139], v[196:199]
	v_mfma_f32_16x16x32_bf16 v[200:203], v[164:167], v[136:139], v[200:203]
	v_exp_f32_e32 v188, v188
	v_exp_f32_e32 v189, v189
	v_exp_f32_e32 v190, v190
	v_exp_f32_e32 v191, v191
	v_mfma_f32_16x16x32_bf16 v[128:131], v[32:35], v[92:95], v[128:131]
	v_exp_f32_e32 v192, v192
	v_exp_f32_e32 v193, v193
	v_exp_f32_e32 v194, v194
	v_exp_f32_e32 v195, v195
	v_mfma_f32_16x16x32_bf16 v[124:127], v[28:31], v[92:95], v[124:127]
	v_cvt_pk_bf16_f32 v246, v188, v189
	v_cvt_pk_bf16_f32 v247, v190, v191
	v_cvt_pk_bf16_f32 v248, v192, v193
	v_cvt_pk_bf16_f32 v249, v194, v195
	v_mfma_f32_16x16x32_bf16 v[120:123], v[24:27], v[92:95], v[120:123]
	v_add_f32_e32 v188, v188, v189
	v_add_f32_e32 v190, v190, v191
	v_add_f32_e32 v192, v192, v193
	v_add_f32_e32 v194, v194, v195
	v_mfma_f32_16x16x32_bf16 v[116:119], v[20:23], v[92:95], v[116:119]
	v_add_f32_e32 v188, v188, v190
	v_add_f32_e32 v192, v192, v194
	v_add_f32_e32 v188, v188, v192
	v_add_f32_e32 v223, v223, v188
	v_exp_f32_e32 v196, v196
	v_exp_f32_e32 v197, v197
	v_exp_f32_e32 v198, v198
	v_exp_f32_e32 v199, v199
	v_mfma_f32_16x16x32_bf16 v[64:67], v[32:35], v[246:249], v[64:67]
	v_exp_f32_e32 v200, v200
	v_exp_f32_e32 v201, v201
	v_exp_f32_e32 v202, v202
	v_exp_f32_e32 v203, v203
	v_mfma_f32_16x16x32_bf16 v[60:63], v[28:31], v[246:249], v[60:63]
	v_cvt_pk_bf16_f32 v92, v196, v197
	v_cvt_pk_bf16_f32 v93, v198, v199
	v_cvt_pk_bf16_f32 v94, v200, v201
	v_cvt_pk_bf16_f32 v95, v202, v203
	v_mfma_f32_16x16x32_bf16 v[56:59], v[24:27], v[246:249], v[56:59]
	v_add_f32_e32 v196, v196, v197
	v_add_f32_e32 v198, v198, v199
	v_add_f32_e32 v200, v200, v201
	v_add_f32_e32 v202, v202, v203
	v_mfma_f32_16x16x32_bf16 v[52:55], v[20:23], v[246:249], v[52:55]
	v_add_f32_e32 v196, v196, v198
	v_add_f32_e32 v200, v200, v202
	v_add_f32_e32 v196, v196, v200
	v_add_f32_e32 v222, v222, v196
	s_waitcnt lgkmcnt(0)
	v_sub_f32_e32 v212, v212, v239
	v_sub_f32_e32 v213, v213, v239
	v_sub_f32_e32 v214, v214, v239
	v_mfma_f32_16x16x32_bf16 v[96:99], v[32:35], v[92:95], v[96:99]
	v_sub_f32_e32 v215, v215, v239
	v_sub_f32_e32 v242, v242, v239
	v_sub_f32_e32 v243, v243, v239
	v_mfma_f32_16x16x32_bf16 v[88:91], v[28:31], v[92:95], v[88:91]
	v_sub_f32_e32 v244, v244, v239
	v_sub_f32_e32 v245, v245, v239
	v_cndmask_b32_e64 v212, v238, v212, s[0:1]
	v_mfma_f32_16x16x32_bf16 v[72:75], v[24:27], v[92:95], v[72:75]
	v_cndmask_b32_e64 v213, v238, v213, s[6:7]
	v_cndmask_b32_e64 v214, v238, v214, s[8:9]
	v_cndmask_b32_e64 v215, v238, v215, s[10:11]
	v_mfma_f32_16x16x32_bf16 v[68:71], v[20:23], v[92:95], v[68:71]
	v_cndmask_b32_e64 v242, v238, v242, s[12:13]
	v_cndmask_b32_e64 v243, v238, v243, s[14:15]
	v_cndmask_b32_e64 v244, v238, v244, s[16:17]
	v_cndmask_b32_e64 v245, v238, v245, s[18:19]
	v_add_u32_e32 v240, 0x100, v240
	s_add_u32 s21, s92, 3
	s_cmp_lt_u32 s21, s88
	s_cselect_b32 s87, 1, 0
	s_add_u32 s21, s21, s93
	s_lshl_b32 s22, s21, 7
	s_add_u32 s22, s22, s62
	s_lshl_b32 s21, s21, 16
	s_add_u32 s21, s21, s61
	s_add_u32 s84, s95, s94
	s_add_u32 s92, s92, 1
	s_add_u32 s63, s63, 1
	s_cmp_eq_u32 s63, 3
	s_cselect_b32 s63, 0, s63
	s_lshl_b32 s95, s63, 14
	s_lshr_b32 s20, s63, 1
	s_lshl_b32 s20, s20, 4
	s_add_u32 s95, s95, s20
	s_add_u32 s95, s95, 0x18000
	s_sub_i32 s80, s92, s60
	s_sub_i32 s89, s92, s76
	s_cmp_lt_i32 s80, 0
	s_cselect_b32 s89, s92, s89
	s_max_i32 s89, s89, 0
	s_min_i32 s89, s89, 7
	s_lshr_b32 s81, s89, 1
	s_lshl_b32 s81, s81, 14
	s_add_u32 s81, s81, 0x8000
	s_and_b32 s82, s89, 1
	s_lshl_b32 s20, s82, 8
	s_add_u32 s23, s81, s20
	s_lshl_b32 s20, s82, 10
	s_add_u32 s33, s81, s20
	s_add_u32 s33, s33, 0x2000
	s_cmp_ge_i32 s80, 0
	s_cselect_b32 s20, 1, 0
	s_cmp_lt_i32 s80, s76
	s_cselect_b32 s20, s20, 0
	s_cmp_lg_u32 s20, 0
	s_cbranch_scc0 .Latt_cs14
	s_add_u32 s23, s95, s97
	s_add_u32 s33, s95, s90

.Latt_sk13:
	v_add_u32_e32 v251, s23, v233
	v_add_u32_e32 v253, s33, v234
	ds_read_b128 v[176:179], v251 offset:0
	ds_read_b128 v[168:171], v251 offset:4096
	ds_read_b128 v[172:175], v251 offset:2048
	ds_read_b128 v[164:167], v251 offset:6144
	ds_read_b128 v[32:35], v253 offset:0
	ds_read_b128 v[28:31], v253 offset:2048
	ds_read_b128 v[24:27], v253 offset:4096
	ds_read_b128 v[20:23], v253 offset:6144
	v_mfma_f32_16x16x32_bf16 v[188:191], v[48:51], v[156:159], v[180:183]
	v_mfma_f32_16x16x32_bf16 v[192:195], v[40:43], v[156:159], v[184:187]
	v_mfma_f32_16x16x32_bf16 v[188:191], v[44:47], v[160:163], v[188:191]
	v_mfma_f32_16x16x32_bf16 v[192:195], v[36:39], v[160:163], v[192:195]
	ds_read2_b32 v[180:181], v240 offset0:0 offset1:1
	ds_read2_b32 v[182:183], v240 offset0:2 offset1:3
	ds_read2_b32 v[184:185], v240 offset0:4 offset1:5
	ds_read2_b32 v[186:187], v240 offset0:6 offset1:7
	v_mfma_f32_16x16x32_bf16 v[196:199], v[48:51], v[148:151], v[80:83]
	v_mfma_f32_16x16x32_bf16 v[200:203], v[40:43], v[148:151], v[84:87]
	v_mfma_f32_16x16x32_bf16 v[196:199], v[44:47], v[152:155], v[196:199]
	v_mfma_f32_16x16x32_bf16 v[200:203], v[36:39], v[152:155], v[200:203]
	v_exp_f32_e32 v188, v188
	v_exp_f32_e32 v189, v189
	v_exp_f32_e32 v190, v190
	v_exp_f32_e32 v191, v191
	v_exp_f32_e32 v192, v192
	v_exp_f32_e32 v193, v193
	v_exp_f32_e32 v194, v194
	v_exp_f32_e32 v195, v195
	v_cvt_pk_bf16_f32 v246, v188, v189
	v_cvt_pk_bf16_f32 v247, v190, v191
	v_cvt_pk_bf16_f32 v248, v192, v193
	v_cvt_pk_bf16_f32 v249, v194, v195
	v_add_f32_e32 v188, v188, v189
	v_add_f32_e32 v190, v190, v191
	v_add_f32_e32 v192, v192, v193
	v_add_f32_e32 v194, v194, v195
	v_add_f32_e32 v188, v188, v190
	v_add_f32_e32 v192, v192, v194
	v_add_f32_e32 v188, v188, v192
	v_add_f32_e32 v225, v225, v188
	v_mfma_f32_16x16x32_bf16 v[188:191], v[48:51], v[140:143], v[204:207]
	v_mfma_f32_16x16x32_bf16 v[192:195], v[40:43], v[140:143], v[208:211]
	v_mfma_f32_16x16x32_bf16 v[188:191], v[44:47], v[144:147], v[188:191]
	v_mfma_f32_16x16x32_bf16 v[192:195], v[36:39], v[144:147], v[192:195]
	v_exp_f32_e32 v196, v196
	v_exp_f32_e32 v197, v197
	v_exp_f32_e32 v198, v198
	v_exp_f32_e32 v199, v199
	v_mfma_f32_16x16x32_bf16 v[112:115], v[16:19], v[246:249], v[112:115]
	v_exp_f32_e32 v200, v200
	v_exp_f32_e32 v201, v201
	v_exp_f32_e32 v202, v202
	v_exp_f32_e32 v203, v203
	v_mfma_f32_16x16x32_bf16 v[108:111], v[12:15], v[246:249], v[108:111]
	v_cvt_pk_bf16_f32 v92, v196, v197
	v_cvt_pk_bf16_f32 v93, v198, v199
	v_cvt_pk_bf16_f32 v94, v200, v201
	v_cvt_pk_bf16_f32 v95, v202, v203
	v_mfma_f32_16x16x32_bf16 v[104:107], v[8:11], v[246:249], v[104:107]
	v_add_f32_e32 v196, v196, v197
	v_add_f32_e32 v198, v198, v199
	v_add_f32_e32 v200, v200, v201
	v_add_f32_e32 v202, v202, v203
	v_mfma_f32_16x16x32_bf16 v[100:103], v[4:7], v[246:249], v[100:103]
	v_add_f32_e32 v196, v196, v198
	v_add_f32_e32 v200, v200, v202
	v_add_f32_e32 v196, v196, v200
	v_add_f32_e32 v224, v224, v196
	v_mfma_f32_16x16x32_bf16 v[196:199], v[48:51], v[132:135], v[212:215]
	v_mfma_f32_16x16x32_bf16 v[200:203], v[40:43], v[132:135], v[242:245]
	v_mfma_f32_16x16x32_bf16 v[196:199], v[44:47], v[136:139], v[196:199]
	v_mfma_f32_16x16x32_bf16 v[200:203], v[36:39], v[136:139], v[200:203]
	v_exp_f32_e32 v188, v188
	v_exp_f32_e32 v189, v189
	v_exp_f32_e32 v190, v190
	v_exp_f32_e32 v191, v191
	v_mfma_f32_16x16x32_bf16 v[128:131], v[16:19], v[92:95], v[128:131]
	v_exp_f32_e32 v192, v192
	v_exp_f32_e32 v193, v193
	v_exp_f32_e32 v194, v194
	v_exp_f32_e32 v195, v195
	v_mfma_f32_16x16x32_bf16 v[124:127], v[12:15], v[92:95], v[124:127]
	v_cvt_pk_bf16_f32 v246, v188, v189
	v_cvt_pk_bf16_f32 v247, v190, v191
	v_cvt_pk_bf16_f32 v248, v192, v193
	v_cvt_pk_bf16_f32 v249, v194, v195
	v_mfma_f32_16x16x32_bf16 v[120:123], v[8:11], v[92:95], v[120:123]
	v_add_f32_e32 v188, v188, v189
	v_add_f32_e32 v190, v190, v191
	v_add_f32_e32 v192, v192, v193
	v_add_f32_e32 v194, v194, v195
	v_mfma_f32_16x16x32_bf16 v[116:119], v[4:7], v[92:95], v[116:119]
	v_add_f32_e32 v188, v188, v190
	v_add_f32_e32 v192, v192, v194
	v_add_f32_e32 v188, v188, v192
	v_add_f32_e32 v223, v223, v188
	v_exp_f32_e32 v196, v196
	v_exp_f32_e32 v197, v197
	v_exp_f32_e32 v198, v198
	v_exp_f32_e32 v199, v199
	v_mfma_f32_16x16x32_bf16 v[64:67], v[16:19], v[246:249], v[64:67]
	v_exp_f32_e32 v200, v200
	v_exp_f32_e32 v201, v201
	v_exp_f32_e32 v202, v202
	v_exp_f32_e32 v203, v203
	v_mfma_f32_16x16x32_bf16 v[60:63], v[12:15], v[246:249], v[60:63]
	v_cvt_pk_bf16_f32 v92, v196, v197
	v_cvt_pk_bf16_f32 v93, v198, v199
	v_cvt_pk_bf16_f32 v94, v200, v201
	v_cvt_pk_bf16_f32 v95, v202, v203
	v_mfma_f32_16x16x32_bf16 v[56:59], v[8:11], v[246:249], v[56:59]
	v_add_f32_e32 v196, v196, v197
	v_add_f32_e32 v198, v198, v199
	v_add_f32_e32 v200, v200, v201
	v_add_f32_e32 v202, v202, v203
	v_mfma_f32_16x16x32_bf16 v[52:55], v[4:7], v[246:249], v[52:55]
	v_add_f32_e32 v196, v196, v198
	v_add_f32_e32 v200, v200, v202
	v_add_f32_e32 v196, v196, v200
	v_add_f32_e32 v222, v222, v196
	s_waitcnt lgkmcnt(0)
	v_sub_f32_e32 v180, v180, v239
	v_sub_f32_e32 v181, v181, v239
	v_sub_f32_e32 v182, v182, v239
	v_mfma_f32_16x16x32_bf16 v[96:99], v[16:19], v[92:95], v[96:99]
	v_sub_f32_e32 v183, v183, v239
	v_sub_f32_e32 v184, v184, v239
	v_sub_f32_e32 v185, v185, v239
	v_mfma_f32_16x16x32_bf16 v[88:91], v[12:15], v[92:95], v[88:91]
	v_sub_f32_e32 v186, v186, v239
	v_sub_f32_e32 v187, v187, v239
	v_cndmask_b32_e64 v180, v238, v180, s[0:1]
	v_mfma_f32_16x16x32_bf16 v[72:75], v[8:11], v[92:95], v[72:75]
	v_cndmask_b32_e64 v181, v238, v181, s[6:7]
	v_cndmask_b32_e64 v182, v238, v182, s[8:9]
	v_cndmask_b32_e64 v183, v238, v183, s[10:11]
	v_mfma_f32_16x16x32_bf16 v[68:71], v[4:7], v[92:95], v[68:71]
	v_cndmask_b32_e64 v184, v238, v184, s[12:13]
	v_cndmask_b32_e64 v185, v238, v185, s[14:15]
	v_cndmask_b32_e64 v186, v238, v186, s[16:17]
	v_cndmask_b32_e64 v187, v238, v187, s[18:19]
	v_add_u32_e32 v240, 0x100, v240
	s_add_u32 s21, s92, 3
	s_cmp_lt_u32 s21, s88
	s_cselect_b32 s87, 1, 0
	s_add_u32 s21, s21, s93
	s_lshl_b32 s22, s21, 7
	s_add_u32 s22, s22, s62
	s_lshl_b32 s21, s21, 16
	s_add_u32 s21, s21, s61
	s_add_u32 s84, s95, s94
	s_add_u32 s92, s92, 1
	s_add_u32 s63, s63, 1
	s_cmp_eq_u32 s63, 3
	s_cselect_b32 s63, 0, s63
	s_lshl_b32 s95, s63, 14
	s_lshr_b32 s20, s63, 1
	s_lshl_b32 s20, s20, 4
	s_add_u32 s95, s95, s20
	s_add_u32 s95, s95, 0x18000
	s_sub_i32 s80, s92, s60
	s_sub_i32 s89, s92, s76
	s_cmp_lt_i32 s80, 0
	s_cselect_b32 s89, s92, s89
	s_max_i32 s89, s89, 0
	s_min_i32 s89, s89, 7
	s_lshr_b32 s81, s89, 1
	s_lshl_b32 s81, s81, 14
	s_add_u32 s81, s81, 0x8000
	s_and_b32 s82, s89, 1
	s_lshl_b32 s20, s82, 8
	s_add_u32 s23, s81, s20
	s_lshl_b32 s20, s82, 10
	s_add_u32 s33, s81, s20
	s_add_u32 s33, s33, 0x2000
	s_cmp_ge_i32 s80, 0
	s_cselect_b32 s20, 1, 0
	s_cmp_lt_i32 s80, s76
	s_cselect_b32 s20, s20, 0
	s_cmp_lg_u32 s20, 0
	s_cbranch_scc0 .Latt_cs16
	s_add_u32 s23, s95, s97
	s_add_u32 s33, s95, s90

.Latt_sk15:
	v_add_u32_e32 v251, s23, v233
	v_add_u32_e32 v253, s33, v234
	ds_read_b128 v[48:51], v251 offset:0
	ds_read_b128 v[40:43], v251 offset:4096
	ds_read_b128 v[44:47], v251 offset:2048
	ds_read_b128 v[36:39], v251 offset:6144
	ds_read_b128 v[16:19], v253 offset:0
	ds_read_b128 v[12:15], v253 offset:2048
	ds_read_b128 v[8:11], v253 offset:4096
	ds_read_b128 v[4:7], v253 offset:6144
	v_mfma_f32_16x16x32_bf16 v[188:191], v[176:179], v[156:159], v[80:83]
	v_mfma_f32_16x16x32_bf16 v[192:195], v[168:171], v[156:159], v[84:87]
	v_mfma_f32_16x16x32_bf16 v[188:191], v[172:175], v[160:163], v[188:191]
	v_mfma_f32_16x16x32_bf16 v[192:195], v[164:167], v[160:163], v[192:195]
	ds_read2_b32 v[80:81], v240 offset0:0 offset1:1
	ds_read2_b32 v[82:83], v240 offset0:2 offset1:3
	ds_read2_b32 v[84:85], v240 offset0:4 offset1:5
	ds_read2_b32 v[86:87], v240 offset0:6 offset1:7
	v_mfma_f32_16x16x32_bf16 v[196:199], v[176:179], v[148:151], v[204:207]
	v_mfma_f32_16x16x32_bf16 v[200:203], v[168:171], v[148:151], v[208:211]
	v_mfma_f32_16x16x32_bf16 v[196:199], v[172:175], v[152:155], v[196:199]
	v_mfma_f32_16x16x32_bf16 v[200:203], v[164:167], v[152:155], v[200:203]
	v_exp_f32_e32 v188, v188
	v_exp_f32_e32 v189, v189
	v_exp_f32_e32 v190, v190
	v_exp_f32_e32 v191, v191
	v_exp_f32_e32 v192, v192
	v_exp_f32_e32 v193, v193
	v_exp_f32_e32 v194, v194
	v_exp_f32_e32 v195, v195
	v_cvt_pk_bf16_f32 v246, v188, v189
	v_cvt_pk_bf16_f32 v247, v190, v191
	v_cvt_pk_bf16_f32 v248, v192, v193
	v_cvt_pk_bf16_f32 v249, v194, v195
	v_add_f32_e32 v188, v188, v189
	v_add_f32_e32 v190, v190, v191
	v_add_f32_e32 v192, v192, v193
	v_add_f32_e32 v194, v194, v195
	v_add_f32_e32 v188, v188, v190
	v_add_f32_e32 v192, v192, v194
	v_add_f32_e32 v188, v188, v192
	v_add_f32_e32 v225, v225, v188
	v_mfma_f32_16x16x32_bf16 v[188:191], v[176:179], v[140:143], v[212:215]
	v_mfma_f32_16x16x32_bf16 v[192:195], v[168:171], v[140:143], v[242:245]
	v_mfma_f32_16x16x32_bf16 v[188:191], v[172:175], v[144:147], v[188:191]
	v_mfma_f32_16x16x32_bf16 v[192:195], v[164:167], v[144:147], v[192:195]
	v_exp_f32_e32 v196, v196
	v_exp_f32_e32 v197, v197
	v_exp_f32_e32 v198, v198
	v_exp_f32_e32 v199, v199
	v_mfma_f32_16x16x32_bf16 v[112:115], v[32:35], v[246:249], v[112:115]
	v_exp_f32_e32 v200, v200
	v_exp_f32_e32 v201, v201
	v_exp_f32_e32 v202, v202
	v_exp_f32_e32 v203, v203
	v_mfma_f32_16x16x32_bf16 v[108:111], v[28:31], v[246:249], v[108:111]
	v_cvt_pk_bf16_f32 v92, v196, v197
	v_cvt_pk_bf16_f32 v93, v198, v199
	v_cvt_pk_bf16_f32 v94, v200, v201
	v_cvt_pk_bf16_f32 v95, v202, v203
	v_mfma_f32_16x16x32_bf16 v[104:107], v[24:27], v[246:249], v[104:107]
	v_add_f32_e32 v196, v196, v197
	v_add_f32_e32 v198, v198, v199
	v_add_f32_e32 v200, v200, v201
	v_add_f32_e32 v202, v202, v203
	v_mfma_f32_16x16x32_bf16 v[100:103], v[20:23], v[246:249], v[100:103]
	v_add_f32_e32 v196, v196, v198
	v_add_f32_e32 v200, v200, v202
	v_add_f32_e32 v196, v196, v200
	v_add_f32_e32 v224, v224, v196
	v_mfma_f32_16x16x32_bf16 v[196:199], v[176:179], v[132:135], v[180:183]
	v_mfma_f32_16x16x32_bf16 v[200:203], v[168:171], v[132:135], v[184:187]
	v_mfma_f32_16x16x32_bf16 v[196:199], v[172:175], v[136:139], v[196:199]
	v_mfma_f32_16x16x32_bf16 v[200:203], v[164:167], v[136:139], v[200:203]
	v_exp_f32_e32 v188, v188
	v_exp_f32_e32 v189, v189
	v_exp_f32_e32 v190, v190
	v_exp_f32_e32 v191, v191
	v_mfma_f32_16x16x32_bf16 v[128:131], v[32:35], v[92:95], v[128:131]
	v_exp_f32_e32 v192, v192
	v_exp_f32_e32 v193, v193
	v_exp_f32_e32 v194, v194
	v_exp_f32_e32 v195, v195
	v_mfma_f32_16x16x32_bf16 v[124:127], v[28:31], v[92:95], v[124:127]
	v_cvt_pk_bf16_f32 v246, v188, v189
	v_cvt_pk_bf16_f32 v247, v190, v191
	v_cvt_pk_bf16_f32 v248, v192, v193
	v_cvt_pk_bf16_f32 v249, v194, v195
	v_mfma_f32_16x16x32_bf16 v[120:123], v[24:27], v[92:95], v[120:123]
	v_add_f32_e32 v188, v188, v189
	v_add_f32_e32 v190, v190, v191
	v_add_f32_e32 v192, v192, v193
	v_add_f32_e32 v194, v194, v195
	v_mfma_f32_16x16x32_bf16 v[116:119], v[20:23], v[92:95], v[116:119]
	v_add_f32_e32 v188, v188, v190
	v_add_f32_e32 v192, v192, v194
	v_add_f32_e32 v188, v188, v192
	v_add_f32_e32 v223, v223, v188
	v_exp_f32_e32 v196, v196
	v_exp_f32_e32 v197, v197
	v_exp_f32_e32 v198, v198
	v_exp_f32_e32 v199, v199
	v_mfma_f32_16x16x32_bf16 v[64:67], v[32:35], v[246:249], v[64:67]
	v_exp_f32_e32 v200, v200
	v_exp_f32_e32 v201, v201
	v_exp_f32_e32 v202, v202
	v_exp_f32_e32 v203, v203
	v_mfma_f32_16x16x32_bf16 v[60:63], v[28:31], v[246:249], v[60:63]
	v_cvt_pk_bf16_f32 v92, v196, v197
	v_cvt_pk_bf16_f32 v93, v198, v199
	v_cvt_pk_bf16_f32 v94, v200, v201
	v_cvt_pk_bf16_f32 v95, v202, v203
	v_mfma_f32_16x16x32_bf16 v[56:59], v[24:27], v[246:249], v[56:59]
	v_add_f32_e32 v196, v196, v197
	v_add_f32_e32 v198, v198, v199
	v_add_f32_e32 v200, v200, v201
	v_add_f32_e32 v202, v202, v203
	v_mfma_f32_16x16x32_bf16 v[52:55], v[20:23], v[246:249], v[52:55]
	v_add_f32_e32 v196, v196, v198
	v_add_f32_e32 v200, v200, v202
	v_add_f32_e32 v196, v196, v200
	v_add_f32_e32 v222, v222, v196
	s_waitcnt lgkmcnt(0)
	v_sub_f32_e32 v80, v80, v239
	v_sub_f32_e32 v81, v81, v239
	v_sub_f32_e32 v82, v82, v239
	v_mfma_f32_16x16x32_bf16 v[96:99], v[32:35], v[92:95], v[96:99]
	v_sub_f32_e32 v83, v83, v239
	v_sub_f32_e32 v84, v84, v239
	v_sub_f32_e32 v85, v85, v239
	v_mfma_f32_16x16x32_bf16 v[88:91], v[28:31], v[92:95], v[88:91]
	v_sub_f32_e32 v86, v86, v239
	v_sub_f32_e32 v87, v87, v239
	v_cndmask_b32_e64 v80, v238, v80, s[0:1]
	v_mfma_f32_16x16x32_bf16 v[72:75], v[24:27], v[92:95], v[72:75]
	v_cndmask_b32_e64 v81, v238, v81, s[6:7]
	v_cndmask_b32_e64 v82, v238, v82, s[8:9]
	v_cndmask_b32_e64 v83, v238, v83, s[10:11]
	v_mfma_f32_16x16x32_bf16 v[68:71], v[20:23], v[92:95], v[68:71]
	v_cndmask_b32_e64 v84, v238, v84, s[12:13]
	v_cndmask_b32_e64 v85, v238, v85, s[14:15]
	v_cndmask_b32_e64 v86, v238, v86, s[16:17]
	v_cndmask_b32_e64 v87, v238, v87, s[18:19]
	v_add_u32_e32 v240, 0x100, v240
	s_add_u32 s21, s92, 3
	s_cmp_lt_u32 s21, s88
	s_cselect_b32 s87, 1, 0
	s_add_u32 s21, s21, s93
	s_lshl_b32 s22, s21, 7
	s_add_u32 s22, s22, s62
	s_lshl_b32 s21, s21, 16
	s_add_u32 s21, s21, s61
	s_add_u32 s84, s95, s94
	s_add_u32 s92, s92, 1
	s_add_u32 s63, s63, 1
	s_cmp_eq_u32 s63, 3
	s_cselect_b32 s63, 0, s63
	s_lshl_b32 s95, s63, 14
	s_lshr_b32 s20, s63, 1
	s_lshl_b32 s20, s20, 4
	s_add_u32 s95, s95, s20
	s_add_u32 s95, s95, 0x18000
	s_sub_i32 s80, s92, s60
	s_sub_i32 s89, s92, s76
	s_cmp_lt_i32 s80, 0
	s_cselect_b32 s89, s92, s89
	s_max_i32 s89, s89, 0
	s_min_i32 s89, s89, 7
	s_lshr_b32 s81, s89, 1
	s_lshl_b32 s81, s81, 14
	s_add_u32 s81, s81, 0x8000
	s_and_b32 s82, s89, 1
	s_lshl_b32 s20, s82, 8
	s_add_u32 s23, s81, s20
	s_lshl_b32 s20, s82, 10
	s_add_u32 s33, s81, s20
	s_add_u32 s33, s33, 0x2000
	s_cmp_ge_i32 s80, 0
	s_cselect_b32 s20, 1, 0
	s_cmp_lt_i32 s80, s76
	s_cselect_b32 s20, s20, 0
	s_cmp_lg_u32 s20, 0
	s_cbranch_scc0 .Latt_cs18
	s_add_u32 s23, s95, s97
	s_add_u32 s33, s95, s90

.Latt_sk17:
	v_add_u32_e32 v251, s23, v233
	v_add_u32_e32 v253, s33, v234
	ds_read_b128 v[176:179], v251 offset:0
	ds_read_b128 v[168:171], v251 offset:4096
	ds_read_b128 v[172:175], v251 offset:2048
	ds_read_b128 v[164:167], v251 offset:6144
	ds_read_b128 v[32:35], v253 offset:0
	ds_read_b128 v[28:31], v253 offset:2048
	ds_read_b128 v[24:27], v253 offset:4096
	ds_read_b128 v[20:23], v253 offset:6144
	v_mfma_f32_16x16x32_bf16 v[188:191], v[48:51], v[156:159], v[204:207]
	v_mfma_f32_16x16x32_bf16 v[192:195], v[40:43], v[156:159], v[208:211]
	v_mfma_f32_16x16x32_bf16 v[188:191], v[44:47], v[160:163], v[188:191]
	v_mfma_f32_16x16x32_bf16 v[192:195], v[36:39], v[160:163], v[192:195]
	v_mfma_f32_16x16x32_bf16 v[196:199], v[48:51], v[148:151], v[212:215]
	v_mfma_f32_16x16x32_bf16 v[200:203], v[40:43], v[148:151], v[242:245]
	v_mfma_f32_16x16x32_bf16 v[196:199], v[44:47], v[152:155], v[196:199]
	v_mfma_f32_16x16x32_bf16 v[200:203], v[36:39], v[152:155], v[200:203]
	s_nop 2
	v_exp_f32_e32 v188, v188
	v_exp_f32_e32 v189, v189
	v_exp_f32_e32 v190, v190
	v_exp_f32_e32 v191, v191
	v_exp_f32_e32 v192, v192
	v_exp_f32_e32 v193, v193
	v_exp_f32_e32 v194, v194
	v_exp_f32_e32 v195, v195
	v_cvt_pk_bf16_f32 v246, v188, v189
	v_cvt_pk_bf16_f32 v247, v190, v191
	v_cvt_pk_bf16_f32 v248, v192, v193
	v_cvt_pk_bf16_f32 v249, v194, v195
	v_add_f32_e32 v188, v188, v189
	v_add_f32_e32 v190, v190, v191
	v_add_f32_e32 v192, v192, v193
	v_add_f32_e32 v194, v194, v195
	v_add_f32_e32 v188, v188, v190
	v_add_f32_e32 v192, v192, v194
	v_add_f32_e32 v188, v188, v192
	v_add_f32_e32 v225, v225, v188
	v_mfma_f32_16x16x32_bf16 v[188:191], v[48:51], v[140:143], v[180:183]
	v_mfma_f32_16x16x32_bf16 v[192:195], v[40:43], v[140:143], v[184:187]
	v_mfma_f32_16x16x32_bf16 v[188:191], v[44:47], v[144:147], v[188:191]
	v_mfma_f32_16x16x32_bf16 v[192:195], v[36:39], v[144:147], v[192:195]
	v_exp_f32_e32 v196, v196
	v_exp_f32_e32 v197, v197
	v_exp_f32_e32 v198, v198
	v_exp_f32_e32 v199, v199
	v_mfma_f32_16x16x32_bf16 v[112:115], v[16:19], v[246:249], v[112:115]
	v_exp_f32_e32 v200, v200
	v_exp_f32_e32 v201, v201
	v_exp_f32_e32 v202, v202
	v_exp_f32_e32 v203, v203
	v_mfma_f32_16x16x32_bf16 v[108:111], v[12:15], v[246:249], v[108:111]
	v_cvt_pk_bf16_f32 v92, v196, v197
	v_cvt_pk_bf16_f32 v93, v198, v199
	v_cvt_pk_bf16_f32 v94, v200, v201
	v_cvt_pk_bf16_f32 v95, v202, v203
	v_mfma_f32_16x16x32_bf16 v[104:107], v[8:11], v[246:249], v[104:107]
	v_add_f32_e32 v196, v196, v197
	v_add_f32_e32 v198, v198, v199
	v_add_f32_e32 v200, v200, v201
	v_add_f32_e32 v202, v202, v203
	v_mfma_f32_16x16x32_bf16 v[100:103], v[4:7], v[246:249], v[100:103]
	v_add_f32_e32 v196, v196, v198
	v_add_f32_e32 v200, v200, v202
	v_add_f32_e32 v196, v196, v200
	v_add_f32_e32 v224, v224, v196
	v_mfma_f32_16x16x32_bf16 v[196:199], v[48:51], v[132:135], v[80:83]
	v_mfma_f32_16x16x32_bf16 v[200:203], v[40:43], v[132:135], v[84:87]
	v_mfma_f32_16x16x32_bf16 v[196:199], v[44:47], v[136:139], v[196:199]
	v_mfma_f32_16x16x32_bf16 v[200:203], v[36:39], v[136:139], v[200:203]
	v_exp_f32_e32 v188, v188
	v_exp_f32_e32 v189, v189
	v_exp_f32_e32 v190, v190
	v_exp_f32_e32 v191, v191
	v_mfma_f32_16x16x32_bf16 v[128:131], v[16:19], v[92:95], v[128:131]
	v_exp_f32_e32 v192, v192
	v_exp_f32_e32 v193, v193
	v_exp_f32_e32 v194, v194
	v_exp_f32_e32 v195, v195
	v_mfma_f32_16x16x32_bf16 v[124:127], v[12:15], v[92:95], v[124:127]
	v_cvt_pk_bf16_f32 v246, v188, v189
	v_cvt_pk_bf16_f32 v247, v190, v191
	v_cvt_pk_bf16_f32 v248, v192, v193
	v_cvt_pk_bf16_f32 v249, v194, v195
	v_mfma_f32_16x16x32_bf16 v[120:123], v[8:11], v[92:95], v[120:123]
	v_add_f32_e32 v188, v188, v189
	v_add_f32_e32 v190, v190, v191
	v_add_f32_e32 v192, v192, v193
	v_add_f32_e32 v194, v194, v195
	v_mfma_f32_16x16x32_bf16 v[116:119], v[4:7], v[92:95], v[116:119]
	v_add_f32_e32 v188, v188, v190
	v_add_f32_e32 v192, v192, v194
	v_add_f32_e32 v188, v188, v192
	v_add_f32_e32 v223, v223, v188
	v_exp_f32_e32 v196, v196
	v_exp_f32_e32 v197, v197
	v_exp_f32_e32 v198, v198
	v_exp_f32_e32 v199, v199
	v_mfma_f32_16x16x32_bf16 v[64:67], v[16:19], v[246:249], v[64:67]
	v_exp_f32_e32 v200, v200
	v_exp_f32_e32 v201, v201
	v_exp_f32_e32 v202, v202
	v_exp_f32_e32 v203, v203
	v_mfma_f32_16x16x32_bf16 v[60:63], v[12:15], v[246:249], v[60:63]
	v_cvt_pk_bf16_f32 v92, v196, v197
	v_cvt_pk_bf16_f32 v93, v198, v199
	v_cvt_pk_bf16_f32 v94, v200, v201
	v_cvt_pk_bf16_f32 v95, v202, v203
	v_mfma_f32_16x16x32_bf16 v[56:59], v[8:11], v[246:249], v[56:59]
	v_add_f32_e32 v196, v196, v197
	v_add_f32_e32 v198, v198, v199
	v_add_f32_e32 v200, v200, v201
	v_add_f32_e32 v202, v202, v203
	v_mfma_f32_16x16x32_bf16 v[52:55], v[4:7], v[246:249], v[52:55]
	v_add_f32_e32 v196, v196, v198
	v_add_f32_e32 v200, v200, v202
	v_add_f32_e32 v196, v196, v200
	v_add_f32_e32 v222, v222, v196
	v_mfma_f32_16x16x32_bf16 v[96:99], v[16:19], v[92:95], v[96:99]
	v_mfma_f32_16x16x32_bf16 v[88:91], v[12:15], v[92:95], v[88:91]
	v_mfma_f32_16x16x32_bf16 v[72:75], v[8:11], v[92:95], v[72:75]
	v_mfma_f32_16x16x32_bf16 v[68:71], v[4:7], v[92:95], v[68:71]
	v_add_u32_e32 v240, 0x100, v240
	s_add_u32 s21, s92, 3
	s_cmp_lt_u32 s21, s88
	s_cselect_b32 s87, 1, 0
	s_add_u32 s21, s21, s93
	s_lshl_b32 s22, s21, 7
	s_add_u32 s22, s22, s62
	s_lshl_b32 s21, s21, 16
	s_add_u32 s21, s21, s61
	s_add_u32 s84, s95, s94
	s_add_u32 s92, s92, 1
	s_add_u32 s63, s63, 1
	s_cmp_eq_u32 s63, 3
	s_cselect_b32 s63, 0, s63
	s_lshl_b32 s95, s63, 14
	s_lshr_b32 s20, s63, 1
	s_lshl_b32 s20, s20, 4
	s_add_u32 s95, s95, s20
	s_add_u32 s95, s95, 0x18000
	s_sub_i32 s80, s92, s60
	s_sub_i32 s89, s92, s76
	s_cmp_lt_i32 s80, 0
	s_cselect_b32 s89, s92, s89
	s_max_i32 s89, s89, 0
	s_min_i32 s89, s89, 7
	s_lshr_b32 s81, s89, 1
	s_lshl_b32 s81, s81, 14
	s_add_u32 s81, s81, 0x8000
	s_and_b32 s82, s89, 1
	s_lshl_b32 s20, s82, 8
	s_add_u32 s23, s81, s20
	s_lshl_b32 s20, s82, 10
	s_add_u32 s33, s81, s20
	s_add_u32 s33, s33, 0x2000
	s_cmp_ge_i32 s80, 0
	s_cselect_b32 s20, 1, 0
	s_cmp_lt_i32 s80, s76
	s_cselect_b32 s20, s20, 0
	s_cmp_lg_u32 s20, 0
	s_cbranch_scc0 .Latt_cs20
	s_add_u32 s23, s95, s97
	s_add_u32 s33, s95, s90

.Latt_sk19:
	v_add_u32_e32 v251, s23, v233
	v_add_u32_e32 v253, s33, v234
	ds_read_b128 v[48:51], v251 offset:0
	ds_read_b128 v[40:43], v251 offset:4096
	ds_read_b128 v[44:47], v251 offset:2048
	ds_read_b128 v[36:39], v251 offset:6144
	ds_read_b128 v[16:19], v253 offset:0
	ds_read_b128 v[12:15], v253 offset:2048
	ds_read_b128 v[8:11], v253 offset:4096
	ds_read_b128 v[4:7], v253 offset:6144
	v_mfma_f32_16x16x32_bf16 v[188:191], v[176:179], v[156:159], v[212:215]
	v_mfma_f32_16x16x32_bf16 v[192:195], v[168:171], v[156:159], v[242:245]
	v_mfma_f32_16x16x32_bf16 v[188:191], v[172:175], v[160:163], v[188:191]
	v_mfma_f32_16x16x32_bf16 v[192:195], v[164:167], v[160:163], v[192:195]
	v_mfma_f32_16x16x32_bf16 v[196:199], v[176:179], v[148:151], v[180:183]
	v_mfma_f32_16x16x32_bf16 v[200:203], v[168:171], v[148:151], v[184:187]
	v_mfma_f32_16x16x32_bf16 v[196:199], v[172:175], v[152:155], v[196:199]
	v_mfma_f32_16x16x32_bf16 v[200:203], v[164:167], v[152:155], v[200:203]
	s_nop 2
	v_exp_f32_e32 v188, v188
	v_exp_f32_e32 v189, v189
	v_exp_f32_e32 v190, v190
	v_exp_f32_e32 v191, v191
	v_exp_f32_e32 v192, v192
	v_exp_f32_e32 v193, v193
	v_exp_f32_e32 v194, v194
	v_exp_f32_e32 v195, v195
	v_cvt_pk_bf16_f32 v246, v188, v189
	v_cvt_pk_bf16_f32 v247, v190, v191
	v_cvt_pk_bf16_f32 v248, v192, v193
	v_cvt_pk_bf16_f32 v249, v194, v195
	v_add_f32_e32 v188, v188, v189
	v_add_f32_e32 v190, v190, v191
	v_add_f32_e32 v192, v192, v193
	v_add_f32_e32 v194, v194, v195
	v_add_f32_e32 v188, v188, v190
	v_add_f32_e32 v192, v192, v194
	v_add_f32_e32 v188, v188, v192
	v_add_f32_e32 v225, v225, v188
	v_mfma_f32_16x16x32_bf16 v[188:191], v[176:179], v[140:143], v[80:83]
	v_mfma_f32_16x16x32_bf16 v[192:195], v[168:171], v[140:143], v[84:87]
	v_mfma_f32_16x16x32_bf16 v[188:191], v[172:175], v[144:147], v[188:191]
	v_mfma_f32_16x16x32_bf16 v[192:195], v[164:167], v[144:147], v[192:195]
	v_exp_f32_e32 v196, v196
	v_exp_f32_e32 v197, v197
	v_exp_f32_e32 v198, v198
	v_exp_f32_e32 v199, v199
	v_mfma_f32_16x16x32_bf16 v[112:115], v[32:35], v[246:249], v[112:115]
	v_exp_f32_e32 v200, v200
	v_exp_f32_e32 v201, v201
	v_exp_f32_e32 v202, v202
	v_exp_f32_e32 v203, v203
	v_mfma_f32_16x16x32_bf16 v[108:111], v[28:31], v[246:249], v[108:111]
	v_cvt_pk_bf16_f32 v92, v196, v197
	v_cvt_pk_bf16_f32 v93, v198, v199
	v_cvt_pk_bf16_f32 v94, v200, v201
	v_cvt_pk_bf16_f32 v95, v202, v203
	v_mfma_f32_16x16x32_bf16 v[104:107], v[24:27], v[246:249], v[104:107]
	v_add_f32_e32 v196, v196, v197
	v_add_f32_e32 v198, v198, v199
	v_add_f32_e32 v200, v200, v201
	v_add_f32_e32 v202, v202, v203
	v_mfma_f32_16x16x32_bf16 v[100:103], v[20:23], v[246:249], v[100:103]
	v_add_f32_e32 v196, v196, v198
	v_add_f32_e32 v200, v200, v202
	v_add_f32_e32 v196, v196, v200
	v_add_f32_e32 v224, v224, v196
	v_exp_f32_e32 v188, v188
	v_exp_f32_e32 v189, v189
	v_exp_f32_e32 v190, v190
	v_exp_f32_e32 v191, v191
	v_mfma_f32_16x16x32_bf16 v[128:131], v[32:35], v[92:95], v[128:131]
	v_exp_f32_e32 v192, v192
	v_exp_f32_e32 v193, v193
	v_exp_f32_e32 v194, v194
	v_exp_f32_e32 v195, v195
	v_mfma_f32_16x16x32_bf16 v[124:127], v[28:31], v[92:95], v[124:127]
	v_cvt_pk_bf16_f32 v246, v188, v189
	v_cvt_pk_bf16_f32 v247, v190, v191
	v_cvt_pk_bf16_f32 v248, v192, v193
	v_cvt_pk_bf16_f32 v249, v194, v195
	v_mfma_f32_16x16x32_bf16 v[120:123], v[24:27], v[92:95], v[120:123]
	v_add_f32_e32 v188, v188, v189
	v_add_f32_e32 v190, v190, v191
	v_add_f32_e32 v192, v192, v193
	v_add_f32_e32 v194, v194, v195
	v_mfma_f32_16x16x32_bf16 v[116:119], v[20:23], v[92:95], v[116:119]
	v_add_f32_e32 v188, v188, v190
	v_add_f32_e32 v192, v192, v194
	v_add_f32_e32 v188, v188, v192
	v_add_f32_e32 v223, v223, v188
	v_mfma_f32_16x16x32_bf16 v[64:67], v[32:35], v[246:249], v[64:67]
	v_mfma_f32_16x16x32_bf16 v[60:63], v[28:31], v[246:249], v[60:63]
	v_mfma_f32_16x16x32_bf16 v[56:59], v[24:27], v[246:249], v[56:59]
	v_mfma_f32_16x16x32_bf16 v[52:55], v[20:23], v[246:249], v[52:55]
	v_add_u32_e32 v240, 0x100, v240
	s_add_u32 s21, s92, 3
	s_cmp_lt_u32 s21, s88
	s_cselect_b32 s87, 1, 0
	s_add_u32 s21, s21, s93
	s_lshl_b32 s22, s21, 7
	s_add_u32 s22, s22, s62
	s_lshl_b32 s21, s21, 16
	s_add_u32 s21, s21, s61
	s_add_u32 s84, s95, s94
	s_add_u32 s92, s92, 1
	s_add_u32 s63, s63, 1
	s_cmp_eq_u32 s63, 3
	s_cselect_b32 s63, 0, s63
	s_lshl_b32 s95, s63, 14
	s_lshr_b32 s20, s63, 1
	s_lshl_b32 s20, s20, 4
	s_add_u32 s95, s95, s20
	s_add_u32 s95, s95, 0x18000
	s_sub_i32 s80, s92, s60
	s_sub_i32 s89, s92, s76
	s_cmp_lt_i32 s80, 0
	s_cselect_b32 s89, s92, s89
	s_max_i32 s89, s89, 0
	s_min_i32 s89, s89, 7
	s_lshr_b32 s81, s89, 1
	s_lshl_b32 s81, s81, 14
	s_add_u32 s81, s81, 0x8000
	s_and_b32 s82, s89, 1
	s_lshl_b32 s20, s82, 8
	s_add_u32 s23, s81, s20
	s_lshl_b32 s20, s82, 10
	s_add_u32 s33, s81, s20
	s_add_u32 s33, s33, 0x2000
	s_cmp_ge_i32 s80, 0
	s_cselect_b32 s20, 1, 0
	s_cmp_lt_i32 s80, s76
	s_cselect_b32 s20, s20, 0
	s_cmp_lg_u32 s20, 0
	s_cbranch_scc0 .Latt_cs22
	s_add_u32 s23, s95, s97
	s_add_u32 s33, s95, s90

.Latt_sk21:
	v_add_u32_e32 v251, s23, v233
	v_add_u32_e32 v253, s33, v234
	ds_read_b128 v[176:179], v251 offset:0
	ds_read_b128 v[168:171], v251 offset:4096
	ds_read_b128 v[172:175], v251 offset:2048
	ds_read_b128 v[164:167], v251 offset:6144
	ds_read_b128 v[32:35], v253 offset:0
	ds_read_b128 v[28:31], v253 offset:2048
	ds_read_b128 v[24:27], v253 offset:4096
	ds_read_b128 v[20:23], v253 offset:6144
	v_mfma_f32_16x16x32_bf16 v[188:191], v[48:51], v[156:159], v[180:183]
	v_mfma_f32_16x16x32_bf16 v[192:195], v[40:43], v[156:159], v[184:187]
	v_mfma_f32_16x16x32_bf16 v[188:191], v[44:47], v[160:163], v[188:191]
	v_mfma_f32_16x16x32_bf16 v[192:195], v[36:39], v[160:163], v[192:195]
	v_mfma_f32_16x16x32_bf16 v[196:199], v[48:51], v[148:151], v[80:83]
	v_mfma_f32_16x16x32_bf16 v[200:203], v[40:43], v[148:151], v[84:87]
	v_mfma_f32_16x16x32_bf16 v[196:199], v[44:47], v[152:155], v[196:199]
	v_mfma_f32_16x16x32_bf16 v[200:203], v[36:39], v[152:155], v[200:203]
	s_nop 2
	v_exp_f32_e32 v188, v188
	v_exp_f32_e32 v189, v189
	v_exp_f32_e32 v190, v190
	v_exp_f32_e32 v191, v191
	v_exp_f32_e32 v192, v192
	v_exp_f32_e32 v193, v193
	v_exp_f32_e32 v194, v194
	v_exp_f32_e32 v195, v195
	v_cvt_pk_bf16_f32 v246, v188, v189
	v_cvt_pk_bf16_f32 v247, v190, v191
	v_cvt_pk_bf16_f32 v248, v192, v193
	v_cvt_pk_bf16_f32 v249, v194, v195
	v_add_f32_e32 v188, v188, v189
	v_add_f32_e32 v190, v190, v191
	v_add_f32_e32 v192, v192, v193
	v_add_f32_e32 v194, v194, v195
	v_add_f32_e32 v188, v188, v190
	v_add_f32_e32 v192, v192, v194
	v_add_f32_e32 v188, v188, v192
	v_add_f32_e32 v225, v225, v188
	v_exp_f32_e32 v196, v196
	v_exp_f32_e32 v197, v197
	v_exp_f32_e32 v198, v198
	v_exp_f32_e32 v199, v199
	v_mfma_f32_16x16x32_bf16 v[112:115], v[16:19], v[246:249], v[112:115]
	v_exp_f32_e32 v200, v200
	v_exp_f32_e32 v201, v201
	v_exp_f32_e32 v202, v202
	v_exp_f32_e32 v203, v203
	v_mfma_f32_16x16x32_bf16 v[108:111], v[12:15], v[246:249], v[108:111]
	v_cvt_pk_bf16_f32 v92, v196, v197
	v_cvt_pk_bf16_f32 v93, v198, v199
	v_cvt_pk_bf16_f32 v94, v200, v201
	v_cvt_pk_bf16_f32 v95, v202, v203
	v_mfma_f32_16x16x32_bf16 v[104:107], v[8:11], v[246:249], v[104:107]
	v_add_f32_e32 v196, v196, v197
	v_add_f32_e32 v198, v198, v199
	v_add_f32_e32 v200, v200, v201
	v_add_f32_e32 v202, v202, v203
	v_mfma_f32_16x16x32_bf16 v[100:103], v[4:7], v[246:249], v[100:103]
	v_add_f32_e32 v196, v196, v198
	v_add_f32_e32 v200, v200, v202
	v_add_f32_e32 v196, v196, v200
	v_add_f32_e32 v224, v224, v196
	v_mfma_f32_16x16x32_bf16 v[128:131], v[16:19], v[92:95], v[128:131]
	v_mfma_f32_16x16x32_bf16 v[124:127], v[12:15], v[92:95], v[124:127]
	v_mfma_f32_16x16x32_bf16 v[120:123], v[8:11], v[92:95], v[120:123]
	v_mfma_f32_16x16x32_bf16 v[116:119], v[4:7], v[92:95], v[116:119]
	v_add_u32_e32 v240, 0x100, v240
	s_add_u32 s21, s92, 3
	s_cmp_lt_u32 s21, s88
	s_cselect_b32 s87, 1, 0
	s_add_u32 s21, s21, s93
	s_lshl_b32 s22, s21, 7
	s_add_u32 s22, s22, s62
	s_lshl_b32 s21, s21, 16
	s_add_u32 s21, s21, s61
	s_add_u32 s84, s95, s94
	s_add_u32 s92, s92, 1
	s_add_u32 s63, s63, 1
	s_cmp_eq_u32 s63, 3
	s_cselect_b32 s63, 0, s63
	s_lshl_b32 s95, s63, 14
	s_lshr_b32 s20, s63, 1
	s_lshl_b32 s20, s20, 4
	s_add_u32 s95, s95, s20
	s_add_u32 s95, s95, 0x18000
	s_sub_i32 s80, s92, s60
	s_sub_i32 s89, s92, s76
	s_cmp_lt_i32 s80, 0
	s_cselect_b32 s89, s92, s89
	s_max_i32 s89, s89, 0
	s_min_i32 s89, s89, 7
	s_lshr_b32 s81, s89, 1
	s_lshl_b32 s81, s81, 14
	s_add_u32 s81, s81, 0x8000
	s_and_b32 s82, s89, 1
	s_lshl_b32 s20, s82, 8
	s_add_u32 s23, s81, s20
	s_lshl_b32 s20, s82, 10
	s_add_u32 s33, s81, s20
	s_add_u32 s33, s33, 0x2000
	s_cmp_ge_i32 s80, 0
	s_cselect_b32 s20, 1, 0
	s_cmp_lt_i32 s80, s76
	s_cselect_b32 s20, s20, 0
	s_cmp_lg_u32 s20, 0
	s_cbranch_scc0 .Latt_cs24
	s_add_u32 s23, s95, s97
	s_add_u32 s33, s95, s90

.Latt_F0:
	s_add_u32 s21, s92, 3
	s_cmp_lt_u32 s21, s88
	s_cselect_b32 s87, 1, 0
	s_add_u32 s21, s21, s93
	s_lshl_b32 s22, s21, 7
	s_add_u32 s22, s22, s62
	s_lshl_b32 s21, s21, 16
	s_add_u32 s21, s21, s61
	s_add_u32 s84, s95, s94
	s_add_u32 s92, s92, 1
	s_add_u32 s63, s63, 1
	s_cmp_eq_u32 s63, 3
	s_cselect_b32 s63, 0, s63
	s_lshl_b32 s95, s63, 14
	s_lshr_b32 s20, s63, 1
	s_lshl_b32 s20, s20, 4
	s_add_u32 s95, s95, s20
	s_add_u32 s95, s95, 0x18000
	s_sub_i32 s80, s92, s60
	s_sub_i32 s89, s92, s76
	s_cmp_lt_i32 s80, 0
	s_cselect_b32 s89, s92, s89
	s_max_i32 s89, s89, 0
	s_min_i32 s89, s89, 7
	s_lshr_b32 s81, s89, 1
	s_lshl_b32 s81, s81, 14
	s_add_u32 s81, s81, 0x8000
	s_and_b32 s82, s89, 1
	s_lshl_b32 s20, s82, 8
	s_add_u32 s23, s81, s20
	s_lshl_b32 s20, s82, 10
	s_add_u32 s33, s81, s20
	s_add_u32 s33, s33, 0x2000
	s_cmp_ge_i32 s80, 0
	s_cselect_b32 s20, 1, 0
	s_cmp_lt_i32 s80, s76
	s_cselect_b32 s20, s20, 0
	s_cmp_lg_u32 s20, 0
	s_cbranch_scc0 .Latt_cs26
	s_add_u32 s23, s95, s97
	s_add_u32 s33, s95, s90

.Latt_cdone:
	s_nop 7
	s_cmp_eq_u32 s85, 1
	s_cbranch_scc1 .Latt_went
	s_cmp_eq_u32 s76, 8
	s_cbranch_scc0 .Latt_end
	s_add_u32 s21, s92, 3
	s_cmp_lt_u32 s21, s88
	s_cselect_b32 s87, 1, 0
	s_add_u32 s21, s21, s93
	s_lshl_b32 s22, s21, 7
	s_add_u32 s22, s22, s62
	s_lshl_b32 s21, s21, 16
	s_add_u32 s21, s21, s61
	s_add_u32 s84, s95, s94
	s_add_u32 s92, s92, 1
	s_add_u32 s63, s63, 1
	s_cmp_eq_u32 s63, 3
	s_cselect_b32 s63, 0, s63
	s_lshl_b32 s95, s63, 14
	s_lshr_b32 s20, s63, 1
	s_lshl_b32 s20, s20, 4
	s_add_u32 s95, s95, s20
	s_add_u32 s95, s95, 0x18000
	s_sub_i32 s80, s92, s60
	s_sub_i32 s89, s92, s76
	s_cmp_lt_i32 s80, 0
	s_cselect_b32 s89, s92, s89
	s_max_i32 s89, s89, 0
	s_min_i32 s89, s89, 7
	s_lshr_b32 s81, s89, 1
	s_lshl_b32 s81, s81, 14
	s_add_u32 s81, s81, 0x8000
	s_and_b32 s82, s89, 1
	s_lshl_b32 s20, s82, 8
	s_add_u32 s23, s81, s20
	s_lshl_b32 s20, s82, 10
	s_add_u32 s33, s81, s20
	s_add_u32 s33, s33, 0x2000
	s_cmp_ge_i32 s80, 0
	s_cselect_b32 s20, 1, 0
	s_cmp_lt_i32 s80, s76
	s_cselect_b32 s20, s20, 0
	s_cmp_lg_u32 s20, 0
	s_cbranch_scc0 .Latt_cs38
	s_add_u32 s23, s95, s97
	s_add_u32 s33, s95, s90
